# P3 mid hook: discarded 64-line gather warms L2 with the next stage's gate lines one stage ahead
# baseline (speedup 1.0000x reference)
; __device__ __forceinline__ size_t tm_block(int pm, int ct, int nct) { return ((size_t)pm * nct + ct) * 32768; }
; #define UNPK0(q_) ((f32x4){bf_lo((q_).x), bf_hi((q_).x), bf_lo((q_).y), bf_hi((q_).y)})
; #define UNPK1(q_) ((f32x4){bf_lo((q_).z), bf_hi((q_).z), bf_lo((q_).w), bf_hi((q_).w)})
;     static __device__ __forceinline__ float eneg(float g) { return __builtin_amdgcn_exp2f(-1.4426950408889634f * fminf(fmaxf(g, -30.f), 30.f)); }
;     __device__ __forceinline__ void mid(f32x4 (&acc)[2][2][4][2], const Unit& u, int wr, int wc, int fr, int fq) const {
;     ...
;         const PieceIn pa(scr, Z, tm_block(pm, ga_ct + cb, znct), wr, wc, fr, fq), pb(scr, Z, tm_block(pm, gb_ct + cb, znct), wr, wc, fr, fq);
;         const int col0 = cb * 64 + 8 * fq;
;         f32x4 ba[2][2], bb[2][2];
; #pragma unroll
;         for (int bj = 0; bj < 2; ++bj) { ba[bj][0] = *(const f32x4*)(bg + col0 + bj * 32); ba[bj][1] = *(const f32x4*)(bg + col0 + bj * 32 + 4); bb[bj][0] = *(const f32x4*)(bg + 1024 + col0 + bj * 32); bb[bj][1] = *(const f32x4*)(bg + 1024 + col0 + bj * 32 + 4); }
; #pragma unroll
;         for (int am = 0; am < 4; ++am) { const int ai = am >> 1;
;             u32x4 ra[4][2], rb[4][2];
; #pragma unroll
;             for (int m = 2 * (am & 1); m < 2 * (am & 1) + 2; ++m) { pa.fetch(ai, m, ra[m][0], ra[m][1]); pb.fetch(ai, m, rb[m][0], rb[m][1]); }
;             asm volatile("" ::: "memory");
; #pragma unroll
;             for (int m = 2 * (am & 1); m < 2 * (am & 1) + 2; ++m) {
;                 pa.stage(ra[m][0], ra[m][1]); const u32x4 ga0 = pa.get(0), ga1 = pa.get(1);
;                 asm volatile("" ::: "memory");
;                 pb.stage(rb[m][0], rb[m][1]); const u32x4 gb0 = pb.get(0), gb1 = pb.get(1);
;                 asm volatile("" ::: "memory");
; #pragma unroll
;                 for (int bj = 0; bj < 2; ++bj) { const u32x4 ga = bj ? ga1 : ga0, gb = bj ? gb1 : gb0;
;                     const f32x4 a0 = UNPK0(ga) + ba[bj][0], a1 = UNPK1(ga) + ba[bj][1], b0 = UNPK0(gb) + bb[bj][0], b1 = UNPK1(gb) + bb[bj][1];
; #pragma unroll
;                     for (int k = 0; k < 4; ++k) { acc[ai][bj][m][0][k] *= (1.0f + eneg(b0[k])) * __builtin_amdgcn_rcpf(1.0f + eneg(a0[k]));
;                                                   acc[ai][bj][m][1][k] *= (1.0f + eneg(b1[k])) * __builtin_amdgcn_rcpf(1.0f + eneg(a1[k])); } } }
.LBB0_381:
	s_cmp_lg_u32 s46, 0x40000
	s_cbranch_scc1 .LBB0_380
	v_mov_b32_e32 v3, s26
	v_mov_b32_e32 v136, s44
	v_add_u32_e32 v188, v223, v220
	v_add_u32_e32 v4, 36, v136
	v_ashrrev_i32_e32 v5, 31, v4
	v_mad_i64_i32 v[4:5], s[48:49], v3, s83, v[4:5]
	v_add_u32_e32 v134, 52, v136
	v_ashrrev_i32_e32 v135, 31, v134
	v_lshlrev_b64 v[4:5], 15, v[4:5]
	v_lshl_add_u64 v[186:187], v[208:209], 0, v[4:5]
	v_mad_i64_i32 v[4:5], s[48:49], v3, s83, v[134:135]
	global_load_dwordx4 v[190:193], v[186:187], off
	global_load_dwordx4 v[194:197], v[186:187], off offset:1024
	v_lshlrev_b64 v[4:5], 15, v[4:5]
	v_lshl_add_u64 v[4:5], v[208:209], 0, v[4:5]
	global_load_dwordx4 v[228:231], v[4:5], off
	global_load_dwordx4 v[232:235], v[4:5], off offset:1024
	v_lshl_or_b32 v134, v136, 6, v219
	v_ashrrev_i32_e32 v135, 31, v134
	v_lshlrev_b64 v[134:135], 2, v[134:135]
	v_lshl_add_u64 v[138:139], s[42:43], 0, v[134:135]
	v_add_co_u32_e32 v166, vcc, s84, v138
	v_lshl_add_u64 v[140:141], s[16:17], 0, v[134:135]
	global_load_dwordx4 v[150:153], v[138:139], off offset:16
	global_load_dwordx4 v[158:161], v[138:139], off
	global_load_dwordx4 v[162:165], v[140:141], off
	v_addc_co_u32_e32 v167, vcc, 0, v139, vcc
	global_load_dwordx4 v[154:157], v[166:167], off offset:16
	global_load_dwordx4 v[134:137], v[138:139], off offset:144
	global_load_dwordx4 v[142:145], v[138:139], off offset:128
	global_load_dwordx4 v[146:149], v[140:141], off offset:128
	s_nop 0
	global_load_dwordx4 v[138:141], v[166:167], off offset:144
	global_load_dwordx4 v[174:177], v[186:187], off offset:2048
	global_load_dwordx4 v[178:181], v[186:187], off offset:3072
	s_nop 0
	global_load_dwordx4 v[166:169], v[4:5], off offset:2048
	global_load_dwordx4 v[170:173], v[4:5], off offset:3072
	v_add_u32_e32 v3, v224, v222
	s_waitcnt vmcnt(0)
	v_readfirstlane_b32 s90, v186
	v_readfirstlane_b32 s91, v187
	v_and_b32_e32 v247, 63, v218
	v_lshlrev_b32_e32 v247, 7, v247
	v_lshl_or_b32 v247, v247, 7, v247
	v_and_b32_e32 v247, 0x80f80, v247
	s_add_u32 s90, s90, 0x1000
	s_addc_u32 s91, s91, 0
	global_load_dword v247, v247, s[90:91]
	ds_write_b128 v3, v[190:193]
	ds_write_b128 v3, v[194:197] offset:1152
	ds_read_b128 v[190:193], v188
	ds_read_b128 v[194:197], v188 offset:64
	ds_write_b128 v3, v[228:231]
	ds_write_b128 v3, v[232:235] offset:1152
	ds_read_b128 v[228:231], v188
	ds_read_b128 v[232:235], v188 offset:64
	s_waitcnt lgkmcnt(0)
	v_lshlrev_b32_e32 v189, 16, v190
	v_and_b32_e32 v190, 0xffff0000, v190
	v_lshlrev_b32_e32 v227, 16, v191
	v_and_b32_e32 v237, 0xffff0000, v191
	v_lshlrev_b32_e32 v191, 16, v192
	v_add_f32_e32 v189, v158, v189
	v_and_b32_e32 v192, 0xffff0000, v192
	v_lshlrev_b32_e32 v239, 16, v193
	v_and_b32_e32 v241, 0xffff0000, v193
	v_lshlrev_b32_e32 v193, 16, v228
	v_and_b32_e32 v228, 0xffff0000, v228
	v_lshlrev_b32_e32 v236, 16, v229
	v_and_b32_e32 v242, 0xffff0000, v229
	v_lshlrev_b32_e32 v229, 16, v230
	v_add_f32_e32 v191, v150, v191
	v_add_f32_e32 v190, v159, v190
	v_med3_f32 v189, v189, s85, v226
	v_add_f32_e32 v192, v151, v192
	v_add_f32_e32 v193, v162, v193
	v_add_f32_e32 v229, v154, v229
	v_med3_f32 v191, v191, s85, v226
	v_add_f32_e32 v228, v163, v228
	v_med3_f32 v190, v190, s85, v226
	v_mul_f32_e32 v189, 0xbfb8aa3b, v189
	v_med3_f32 v192, v192, s85, v226
	v_med3_f32 v193, v193, s85, v226
	v_med3_f32 v229, v229, s85, v226
	v_mul_f32_e32 v191, 0xbfb8aa3b, v191
	v_med3_f32 v228, v228, s85, v226
	v_mul_f32_e32 v190, 0xbfb8aa3b, v190
	v_exp_f32_e32 v189, v189
	v_mul_f32_e32 v238, 0xbfb8aa3b, v192
	v_mul_f32_e32 v192, 0xbfb8aa3b, v193
	v_mul_f32_e32 v193, 0xbfb8aa3b, v229
	v_exp_f32_e32 v229, v191
	v_mul_f32_e32 v191, 0xbfb8aa3b, v228
	v_exp_f32_e32 v228, v190
	v_add_f32_e32 v189, 1.0, v189
	v_exp_f32_e32 v190, v192
	v_exp_f32_e32 v192, v193
	v_add_f32_e32 v193, 1.0, v229
	v_add_f32_e32 v229, 1.0, v228
	v_rcp_f32_e32 v228, v189
	v_exp_f32_e32 v189, v238
	v_add_f32_e32 v227, v160, v227
	v_med3_f32 v227, v227, s85, v226
	v_and_b32_e32 v230, 0xffff0000, v230
	v_mul_f32_e32 v227, 0xbfb8aa3b, v227
	v_lshlrev_b32_e32 v240, 16, v231
	v_and_b32_e32 v243, 0xffff0000, v231
	v_add_f32_e32 v231, v155, v230
	v_add_f32_e32 v189, 1.0, v189
	v_exp_f32_e32 v227, v227
	v_rcp_f32_e32 v230, v193
	v_med3_f32 v193, v231, s85, v226
	v_rcp_f32_e32 v231, v189
	v_add_f32_e32 v189, v164, v236
	v_med3_f32 v189, v189, s85, v226
	v_mul_f32_e32 v189, 0xbfb8aa3b, v189
	v_exp_f32_e32 v236, v189
	v_add_f32_e32 v189, 1.0, v227
	v_add_f32_e32 v227, v152, v239
	v_med3_f32 v227, v227, s85, v226
	v_mul_f32_e32 v227, 0xbfb8aa3b, v227
	v_exp_f32_e32 v227, v227
	v_rcp_f32_e32 v238, v189
	v_add_f32_e32 v189, v156, v240
	v_med3_f32 v189, v189, s85, v226
	v_mul_f32_e32 v189, 0xbfb8aa3b, v189
	v_add_f32_e32 v237, v161, v237
	v_exp_f32_e32 v240, v189
	v_add_f32_e32 v189, 1.0, v227
	v_add_f32_e32 v227, v165, v242
	v_med3_f32 v237, v237, s85, v226
	v_med3_f32 v227, v227, s85, v226
	v_mul_f32_e32 v237, 0xbfb8aa3b, v237
	v_exp_f32_e32 v239, v237
	v_mul_f32_e32 v227, 0xbfb8aa3b, v227
	v_exp_f32_e32 v237, v227
	v_add_f32_e32 v227, v153, v241
	v_med3_f32 v227, v227, s85, v226
	v_mul_f32_e32 v227, 0xbfb8aa3b, v227
	v_rcp_f32_e32 v242, v189
	v_add_f32_e32 v189, 1.0, v239
	v_exp_f32_e32 v227, v227
	v_rcp_f32_e32 v239, v189
	v_add_f32_e32 v189, v157, v243
	v_mul_f32_e32 v193, 0xbfb8aa3b, v193
	v_med3_f32 v189, v189, s85, v226
	v_exp_f32_e32 v193, v193
	v_mul_f32_e32 v189, 0xbfb8aa3b, v189
	v_exp_f32_e32 v241, v189
	v_add_f32_e32 v189, 1.0, v227
	v_exp_f32_e32 v191, v191
	v_rcp_f32_e32 v243, v189
	v_lshlrev_b32_e32 v189, 16, v194
	v_rcp_f32_e32 v229, v229
	v_add_f32_e32 v189, v142, v189
	v_pk_add_f32 v[192:193], v[192:193], 1.0 op_sel_hi:[1,0]
; #define UNPK0(q_) ((f32x4){bf_lo((q_).x), bf_hi((q_).x), bf_lo((q_).y), bf_hi((q_).y)})
; #define UNPK1(q_) ((f32x4){bf_lo((q_).z), bf_hi((q_).z), bf_lo((q_).w), bf_hi((q_).w)})
;     static __device__ __forceinline__ float eneg(float g) { return __builtin_amdgcn_exp2f(-1.4426950408889634f * fminf(fmaxf(g, -30.f), 30.f)); }
;     __device__ __forceinline__ void mid(f32x4 (&acc)[2][2][4][2], const Unit& u, int wr, int wc, int fr, int fq) const {
;     ...
;             for (int m = 2 * (am & 1); m < 2 * (am & 1) + 2; ++m) {
;                 pa.stage(ra[m][0], ra[m][1]); const u32x4 ga0 = pa.get(0), ga1 = pa.get(1);
;                 asm volatile("" ::: "memory");
;                 pb.stage(rb[m][0], rb[m][1]); const u32x4 gb0 = pb.get(0), gb1 = pb.get(1);
;                 asm volatile("" ::: "memory");
; #pragma unroll
;                 for (int bj = 0; bj < 2; ++bj) { const u32x4 ga = bj ? ga1 : ga0, gb = bj ? gb1 : gb0;
;                     const f32x4 a0 = UNPK0(ga) + ba[bj][0], a1 = UNPK1(ga) + ba[bj][1], b0 = UNPK0(gb) + bb[bj][0], b1 = UNPK1(gb) + bb[bj][1];
; #pragma unroll
;                     for (int k = 0; k < 4; ++k) { acc[ai][bj][m][0][k] *= (1.0f + eneg(b0[k])) * __builtin_amdgcn_rcpf(1.0f + eneg(a0[k]));
;                                                   acc[ai][bj][m][1][k] *= (1.0f + eneg(b1[k])) * __builtin_amdgcn_rcpf(1.0f + eneg(a1[k])); } } }
	v_med3_f32 v189, v189, s85, v226
	v_pk_mul_f32 v[192:193], v[230:231], v[192:193]
	v_mul_f32_e32 v189, 0xbfb8aa3b, v189
	v_pk_add_f32 v[190:191], v[190:191], 1.0 op_sel_hi:[1,0]
	v_pk_mul_f32 v[126:127], v[126:127], v[192:193]
	v_lshlrev_b32_e32 v193, 16, v196
	v_exp_f32_e32 v189, v189
	v_pk_mul_f32 v[190:191], v[228:229], v[190:191]
	v_add_f32_e32 v193, v134, v193
	v_pk_mul_f32 v[130:131], v[130:131], v[190:191]
	v_pk_add_f32 v[190:191], v[240:241], 1.0 op_sel_hi:[1,0]
	v_med3_f32 v193, v193, s85, v226
	v_pk_mul_f32 v[190:191], v[242:243], v[190:191]
	v_mul_f32_e32 v193, 0xbfb8aa3b, v193
	v_pk_mul_f32 v[128:129], v[128:129], v[190:191]
	v_and_b32_e32 v191, 0xffff0000, v194
	v_lshlrev_b32_e32 v194, 16, v234
	v_add_f32_e32 v189, 1.0, v189
	v_exp_f32_e32 v193, v193
	v_rcp_f32_e32 v192, v189
	v_add_f32_e32 v189, v138, v194
	v_add_f32_e32 v191, v143, v191
	v_pk_add_f32 v[236:237], v[236:237], 1.0 op_sel_hi:[1,0]
	v_med3_f32 v189, v189, s85, v226
	v_med3_f32 v191, v191, s85, v226
	v_pk_mul_f32 v[228:229], v[238:239], v[236:237]
	v_mul_f32_e32 v189, 0xbfb8aa3b, v189
	v_mul_f32_e32 v191, 0xbfb8aa3b, v191
	v_pk_mul_f32 v[132:133], v[132:133], v[228:229]
	v_lshlrev_b32_e32 v227, 16, v195
	v_and_b32_e32 v229, 0xffff0000, v195
	v_and_b32_e32 v195, 0xffff0000, v196
	v_lshlrev_b32_e32 v231, 16, v197
	v_and_b32_e32 v236, 0xffff0000, v197
	v_and_b32_e32 v197, 0xffff0000, v232
	v_exp_f32_e32 v194, v189
	v_add_f32_e32 v189, 1.0, v193
	v_exp_f32_e32 v193, v191
	v_rcp_f32_e32 v196, v189
	v_add_f32_e32 v189, v147, v197
	v_add_f32_e32 v195, v135, v195
	v_med3_f32 v189, v189, s85, v226
	v_med3_f32 v195, v195, s85, v226
	v_mul_f32_e32 v189, 0xbfb8aa3b, v189
	v_mul_f32_e32 v195, 0xbfb8aa3b, v195
	v_and_b32_e32 v230, 0xffff0000, v234
	v_exp_f32_e32 v191, v189
	v_add_f32_e32 v189, 1.0, v193
	v_exp_f32_e32 v197, v195
	v_rcp_f32_e32 v193, v189
	v_add_f32_e32 v189, v139, v230
	v_add_f32_e32 v227, v144, v227
	v_med3_f32 v189, v189, s85, v226
	v_med3_f32 v227, v227, s85, v226
	v_mul_f32_e32 v189, 0xbfb8aa3b, v189
	v_mul_f32_e32 v227, 0xbfb8aa3b, v227
	v_lshlrev_b32_e32 v228, 16, v233
	v_exp_f32_e32 v195, v189
	v_add_f32_e32 v189, 1.0, v197
	v_exp_f32_e32 v227, v227
	v_rcp_f32_e32 v197, v189
	v_add_f32_e32 v189, v148, v228
	v_med3_f32 v189, v189, s85, v226
	v_mul_f32_e32 v189, 0xbfb8aa3b, v189
	v_exp_f32_e32 v228, v189
	v_add_f32_e32 v189, 1.0, v227
	v_add_f32_e32 v227, v136, v231
	v_med3_f32 v227, v227, s85, v226
	v_mul_f32_e32 v227, 0xbfb8aa3b, v227
	v_lshlrev_b32_e32 v190, 16, v232
	v_lshlrev_b32_e32 v232, 16, v235
	v_exp_f32_e32 v227, v227
	v_add_f32_e32 v229, v145, v229
	v_rcp_f32_e32 v230, v189
	v_add_f32_e32 v189, v140, v232
	v_med3_f32 v229, v229, s85, v226
	v_med3_f32 v189, v189, s85, v226
	v_mul_f32_e32 v229, 0xbfb8aa3b, v229
	v_and_b32_e32 v233, 0xffff0000, v233
	v_mul_f32_e32 v189, 0xbfb8aa3b, v189
	v_exp_f32_e32 v231, v229
	v_add_f32_e32 v190, v146, v190
	v_exp_f32_e32 v232, v189
	v_add_f32_e32 v189, 1.0, v227
	v_add_f32_e32 v227, v149, v233
	v_med3_f32 v190, v190, s85, v226
	v_med3_f32 v227, v227, s85, v226
	v_mul_f32_e32 v190, 0xbfb8aa3b, v190
	v_mul_f32_e32 v227, 0xbfb8aa3b, v227
	v_exp_f32_e32 v190, v190
	v_exp_f32_e32 v229, v227
	v_rcp_f32_e32 v234, v189
	v_add_f32_e32 v189, 1.0, v231
	v_rcp_f32_e32 v231, v189
	v_pk_add_f32 v[228:229], v[228:229], 1.0 op_sel_hi:[1,0]
	v_pk_add_f32 v[190:191], v[190:191], 1.0 op_sel_hi:[1,0]
	v_and_b32_e32 v235, 0xffff0000, v235
	v_pk_mul_f32 v[190:191], v[192:193], v[190:191]
	v_pk_mul_f32 v[192:193], v[230:231], v[228:229]
	v_add_f32_e32 v189, v141, v235
	v_pk_mul_f32 v[124:125], v[124:125], v[192:193]
	v_add_f32_e32 v192, v137, v236
	v_med3_f32 v192, v192, s85, v226
	v_mul_f32_e32 v192, 0xbfb8aa3b, v192
	v_exp_f32_e32 v192, v192
	v_med3_f32 v189, v189, s85, v226
	v_mul_f32_e32 v189, 0xbfb8aa3b, v189
	v_exp_f32_e32 v233, v189
	v_add_f32_e32 v189, 1.0, v192
	v_rcp_f32_e32 v235, v189
	ds_write_b128 v3, v[174:177]
	ds_write_b128 v3, v[178:181] offset:1152
	ds_read_b128 v[174:177], v188
	ds_read_b128 v[178:181], v188 offset:64
	ds_write_b128 v3, v[166:169]
	ds_write_b128 v3, v[170:173] offset:1152
	ds_read_b128 v[166:169], v188
	ds_read_b128 v[170:173], v188 offset:64
	v_pk_mul_f32 v[122:123], v[122:123], v[190:191]
	v_pk_add_f32 v[190:191], v[232:233], 1.0 op_sel_hi:[1,0]
	s_waitcnt lgkmcnt(5)
	v_lshlrev_b32_e32 v189, 16, v174
	v_pk_mul_f32 v[190:191], v[234:235], v[190:191]
	s_waitcnt lgkmcnt(1)
; #define UNPK0(q_) ((f32x4){bf_lo((q_).x), bf_hi((q_).x), bf_lo((q_).y), bf_hi((q_).y)})
; #define UNPK1(q_) ((f32x4){bf_lo((q_).z), bf_hi((q_).z), bf_lo((q_).w), bf_hi((q_).w)})
;     static __device__ __forceinline__ float eneg(float g) { return __builtin_amdgcn_exp2f(-1.4426950408889634f * fminf(fmaxf(g, -30.f), 30.f)); }
;     __device__ __forceinline__ void mid(f32x4 (&acc)[2][2][4][2], const Unit& u, int wr, int wc, int fr, int fq) const {
;     ...
;                 for (int bj = 0; bj < 2; ++bj) { const u32x4 ga = bj ? ga1 : ga0, gb = bj ? gb1 : gb0;
;                     const f32x4 a0 = UNPK0(ga) + ba[bj][0], a1 = UNPK1(ga) + ba[bj][1], b0 = UNPK0(gb) + bb[bj][0], b1 = UNPK1(gb) + bb[bj][1];
; #pragma unroll
;                     for (int k = 0; k < 4; ++k) { acc[ai][bj][m][0][k] *= (1.0f + eneg(b0[k])) * __builtin_amdgcn_rcpf(1.0f + eneg(a0[k]));
;                                                   acc[ai][bj][m][1][k] *= (1.0f + eneg(b1[k])) * __builtin_amdgcn_rcpf(1.0f + eneg(a1[k])); } } }
	v_lshlrev_b32_e32 v227, 16, v169
	v_pk_mul_f32 v[120:121], v[120:121], v[190:191]
	v_and_b32_e32 v190, 0xffff0000, v174
	v_lshlrev_b32_e32 v174, 16, v176
	v_and_b32_e32 v228, 0xffff0000, v169
	v_add_f32_e32 v169, v150, v174
	v_pk_add_f32 v[192:193], v[194:195], 1.0 op_sel_hi:[1,0]
	v_med3_f32 v169, v169, s85, v226
	v_pk_mul_f32 v[192:193], v[196:197], v[192:193]
	v_mul_f32_e32 v169, 0xbfb8aa3b, v169
	v_pk_mul_f32 v[118:119], v[118:119], v[192:193]
	v_lshlrev_b32_e32 v191, 16, v175
	v_and_b32_e32 v193, 0xffff0000, v175
	v_and_b32_e32 v175, 0xffff0000, v176
	v_lshlrev_b32_e32 v192, 16, v167
	v_and_b32_e32 v196, 0xffff0000, v167
	v_lshlrev_b32_e32 v167, 16, v168
	v_exp_f32_e32 v169, v169
	v_add_f32_e32 v167, v154, v167
	v_add_f32_e32 v175, v151, v175
	v_med3_f32 v167, v167, s85, v226
	v_med3_f32 v175, v175, s85, v226
	v_mul_f32_e32 v167, 0xbfb8aa3b, v167
	v_mul_f32_e32 v175, 0xbfb8aa3b, v175
	v_and_b32_e32 v197, 0xffff0000, v168
	v_add_f32_e32 v168, v158, v189
	v_exp_f32_e32 v174, v167
	v_add_f32_e32 v167, 1.0, v169
	v_add_f32_e32 v169, v159, v190
	v_exp_f32_e32 v189, v175
	v_add_f32_e32 v190, v160, v191
	v_med3_f32 v190, v190, s85, v226
	v_lshlrev_b32_e32 v194, 16, v177
	v_and_b32_e32 v195, 0xffff0000, v177
	v_lshlrev_b32_e32 v176, 16, v166
	v_and_b32_e32 v177, 0xffff0000, v166
	v_mul_f32_e32 v190, 0xbfb8aa3b, v190
	v_add_f32_e32 v166, v162, v176
	v_rcp_f32_e32 v176, v167
	v_add_f32_e32 v167, v163, v177
	v_add_f32_e32 v177, v155, v197
	v_exp_f32_e32 v191, v190
	v_med3_f32 v175, v177, s85, v226
	v_add_f32_e32 v177, 1.0, v189
	v_add_f32_e32 v189, v164, v192
	v_med3_f32 v189, v189, s85, v226
	v_mul_f32_e32 v189, 0xbfb8aa3b, v189
	v_exp_f32_e32 v190, v189
	v_add_f32_e32 v189, 1.0, v191
	v_add_f32_e32 v191, v152, v194
	v_med3_f32 v191, v191, s85, v226
	v_mul_f32_e32 v191, 0xbfb8aa3b, v191
	v_exp_f32_e32 v191, v191
	v_add_f32_e32 v193, v161, v193
	v_med3_f32 v168, v168, s85, v226
	v_med3_f32 v169, v169, s85, v226
	v_rcp_f32_e32 v192, v189
	v_add_f32_e32 v189, v156, v227
	v_med3_f32 v193, v193, s85, v226
	v_mul_f32_e32 v168, 0xbfb8aa3b, v168
	v_mul_f32_e32 v169, 0xbfb8aa3b, v169
	v_med3_f32 v189, v189, s85, v226
	v_mul_f32_e32 v193, 0xbfb8aa3b, v193
	v_exp_f32_e32 v168, v168
	v_exp_f32_e32 v169, v169
	v_mul_f32_e32 v189, 0xbfb8aa3b, v189
	v_exp_f32_e32 v193, v193
	v_exp_f32_e32 v194, v189
	v_add_f32_e32 v189, 1.0, v191
	v_add_f32_e32 v191, v165, v196
	v_med3_f32 v166, v166, s85, v226
	v_med3_f32 v167, v167, s85, v226
	v_med3_f32 v191, v191, s85, v226
	v_mul_f32_e32 v166, 0xbfb8aa3b, v166
	v_mul_f32_e32 v167, 0xbfb8aa3b, v167
	v_mul_f32_e32 v191, 0xbfb8aa3b, v191
	v_exp_f32_e32 v166, v166
	v_add_f32_e32 v168, 1.0, v168
	v_exp_f32_e32 v167, v167
	v_add_f32_e32 v169, 1.0, v169
	v_exp_f32_e32 v191, v191
	v_rcp_f32_e32 v196, v189
	v_add_f32_e32 v189, 1.0, v193
	v_rcp_f32_e32 v168, v168
	v_rcp_f32_e32 v169, v169
	v_rcp_f32_e32 v193, v189
	v_pk_add_f32 v[190:191], v[190:191], 1.0 op_sel_hi:[1,0]
	v_pk_add_f32 v[166:167], v[166:167], 1.0 op_sel_hi:[1,0]
	v_mul_f32_e32 v175, 0xbfb8aa3b, v175
	v_pk_mul_f32 v[166:167], v[168:169], v[166:167]
	v_pk_mul_f32 v[168:169], v[192:193], v[190:191]
	v_exp_f32_e32 v175, v175
	v_pk_mul_f32 v[116:117], v[116:117], v[168:169]
	v_add_f32_e32 v169, v153, v195
	v_med3_f32 v169, v169, s85, v226
	v_mul_f32_e32 v169, 0xbfb8aa3b, v169
	v_exp_f32_e32 v169, v169
	v_add_f32_e32 v168, v157, v228
	v_med3_f32 v168, v168, s85, v226
	v_mul_f32_e32 v168, 0xbfb8aa3b, v168
	v_rcp_f32_e32 v177, v177
	v_exp_f32_e32 v195, v168
	v_pk_mul_f32 v[114:115], v[114:115], v[166:167]
	v_add_f32_e32 v166, 1.0, v169
	v_rcp_f32_e32 v197, v166
	v_pk_add_f32 v[168:169], v[174:175], 1.0 op_sel_hi:[1,0]
	v_pk_add_f32 v[166:167], v[194:195], 1.0 op_sel_hi:[1,0]
	v_pk_mul_f32 v[168:169], v[176:177], v[168:169]
	v_pk_mul_f32 v[166:167], v[196:197], v[166:167]
	v_pk_mul_f32 v[110:111], v[110:111], v[168:169]
	v_lshlrev_b32_e32 v169, 16, v180
	v_pk_mul_f32 v[112:113], v[112:113], v[166:167]
	v_lshlrev_b32_e32 v166, 16, v178
	v_add_f32_e32 v169, v134, v169
	v_add_f32_e32 v166, v142, v166
	v_med3_f32 v169, v169, s85, v226
	v_med3_f32 v166, v166, s85, v226
	v_mul_f32_e32 v169, 0xbfb8aa3b, v169
	v_mul_f32_e32 v166, 0xbfb8aa3b, v166
	v_exp_f32_e32 v169, v169
	v_and_b32_e32 v167, 0xffff0000, v178
	v_and_b32_e32 v176, 0xffff0000, v180
	s_waitcnt lgkmcnt(0)
; #define UNPK0(q_) ((f32x4){bf_lo((q_).x), bf_hi((q_).x), bf_lo((q_).y), bf_hi((q_).y)})
; #define UNPK1(q_) ((f32x4){bf_lo((q_).z), bf_hi((q_).z), bf_lo((q_).w), bf_hi((q_).w)})
;     static __device__ __forceinline__ float eneg(float g) { return __builtin_amdgcn_exp2f(-1.4426950408889634f * fminf(fmaxf(g, -30.f), 30.f)); }
;     __device__ __forceinline__ void mid(f32x4 (&acc)[2][2][4][2], const Unit& u, int wr, int wc, int fr, int fq) const {
;     ...
;         for (int am = 0; am < 4; ++am) { const int ai = am >> 1;
;             u32x4 ra[4][2], rb[4][2];
; #pragma unroll
;             for (int m = 2 * (am & 1); m < 2 * (am & 1) + 2; ++m) { pa.fetch(ai, m, ra[m][0], ra[m][1]); pb.fetch(ai, m, rb[m][0], rb[m][1]); }
;             asm volatile("" ::: "memory");
; #pragma unroll
;             for (int m = 2 * (am & 1); m < 2 * (am & 1) + 2; ++m) {
;                 pa.stage(ra[m][0], ra[m][1]); const u32x4 ga0 = pa.get(0), ga1 = pa.get(1);
;                 asm volatile("" ::: "memory");
;                 pb.stage(rb[m][0], rb[m][1]); const u32x4 gb0 = pb.get(0), gb1 = pb.get(1);
;                 asm volatile("" ::: "memory");
; #pragma unroll
;                 for (int bj = 0; bj < 2; ++bj) { const u32x4 ga = bj ? ga1 : ga0, gb = bj ? gb1 : gb0;
;                     const f32x4 a0 = UNPK0(ga) + ba[bj][0], a1 = UNPK1(ga) + ba[bj][1], b0 = UNPK0(gb) + bb[bj][0], b1 = UNPK1(gb) + bb[bj][1];
; #pragma unroll
;                     for (int k = 0; k < 4; ++k) { acc[ai][bj][m][0][k] *= (1.0f + eneg(b0[k])) * __builtin_amdgcn_rcpf(1.0f + eneg(a0[k]));
;                                                   acc[ai][bj][m][1][k] *= (1.0f + eneg(b1[k])) * __builtin_amdgcn_rcpf(1.0f + eneg(a1[k])); } } }
	v_lshlrev_b32_e32 v168, 16, v170
	v_and_b32_e32 v178, 0xffff0000, v170
	v_lshlrev_b32_e32 v180, 16, v171
	v_and_b32_e32 v189, 0xffff0000, v171
	v_lshlrev_b32_e32 v170, 16, v172
	v_and_b32_e32 v171, 0xffff0000, v172
	v_exp_f32_e32 v172, v166
	v_add_f32_e32 v168, v146, v168
	v_add_f32_e32 v169, 1.0, v169
	v_med3_f32 v166, v168, s85, v226
	v_add_f32_e32 v168, 1.0, v172
	v_rcp_f32_e32 v172, v169
	v_add_f32_e32 v169, v147, v178
	v_add_co_u32_e32 v178, vcc, s84, v186
	v_lshlrev_b32_e32 v174, 16, v179
	v_and_b32_e32 v175, 0xffff0000, v179
	v_addc_co_u32_e32 v179, vcc, 0, v187, vcc
	global_load_dwordx4 v[190:193], v[178:179], off
	global_load_dwordx4 v[194:197], v[178:179], off offset:1024
	v_add_co_u32_e32 v236, vcc, s84, v4
	v_add_f32_e32 v167, v143, v167
	s_nop 0
	v_addc_co_u32_e32 v237, vcc, 0, v5, vcc
	global_load_dwordx4 v[228:231], v[236:237], off
	global_load_dwordx4 v[232:235], v[236:237], off offset:1024
	v_med3_f32 v167, v167, s85, v226
	v_mul_f32_e32 v167, 0xbfb8aa3b, v167
	v_lshlrev_b32_e32 v227, 16, v173
	v_and_b32_e32 v239, 0xffff0000, v173
	v_exp_f32_e32 v173, v167
	v_add_f32_e32 v174, v144, v174
	v_med3_f32 v174, v174, s85, v226
	v_lshlrev_b32_e32 v177, 16, v181
	v_mul_f32_e32 v174, 0xbfb8aa3b, v174
	v_med3_f32 v167, v169, s85, v226
	v_add_f32_e32 v169, 1.0, v173
	v_add_f32_e32 v173, v135, v176
	v_add_f32_e32 v176, v148, v180
	v_exp_f32_e32 v180, v174
	v_add_f32_e32 v177, v136, v177
	v_med3_f32 v177, v177, s85, v226
	v_add_f32_e32 v175, v145, v175
	v_mul_f32_e32 v177, 0xbfb8aa3b, v177
	v_med3_f32 v175, v175, s85, v226
	v_exp_f32_e32 v177, v177
	v_mul_f32_e32 v175, 0xbfb8aa3b, v175
	v_med3_f32 v174, v176, s85, v226
	v_add_f32_e32 v176, 1.0, v180
	v_add_f32_e32 v180, v140, v227
	v_exp_f32_e32 v227, v175
	v_add_f32_e32 v189, v149, v189
	v_med3_f32 v189, v189, s85, v226
	v_mul_f32_e32 v166, 0xbfb8aa3b, v166
	v_mul_f32_e32 v167, 0xbfb8aa3b, v167
	v_mul_f32_e32 v174, 0xbfb8aa3b, v174
	v_add_f32_e32 v177, 1.0, v177
	v_mul_f32_e32 v175, 0xbfb8aa3b, v189
	v_exp_f32_e32 v166, v166
	v_exp_f32_e32 v167, v167
	v_exp_f32_e32 v174, v174
	v_exp_f32_e32 v175, v175
	v_rcp_f32_e32 v238, v177
	v_add_f32_e32 v177, 1.0, v227
	v_rcp_f32_e32 v168, v168
	v_rcp_f32_e32 v169, v169
	v_rcp_f32_e32 v176, v176
	v_rcp_f32_e32 v177, v177
	v_pk_add_f32 v[174:175], v[174:175], 1.0 op_sel_hi:[1,0]
	v_pk_add_f32 v[166:167], v[166:167], 1.0 op_sel_hi:[1,0]
	v_and_b32_e32 v181, 0xffff0000, v181
	v_pk_mul_f32 v[166:167], v[168:169], v[166:167]
	v_pk_mul_f32 v[168:169], v[176:177], v[174:175]
	v_med3_f32 v173, v173, s85, v226
	v_pk_mul_f32 v[108:109], v[108:109], v[168:169]
	v_add_f32_e32 v169, v137, v181
	v_med3_f32 v169, v169, s85, v226
	v_mul_f32_e32 v173, 0xbfb8aa3b, v173
	v_mul_f32_e32 v169, 0xbfb8aa3b, v169
	v_exp_f32_e32 v173, v173
	v_exp_f32_e32 v169, v169
	v_add_f32_e32 v170, v138, v170
	v_add_f32_e32 v171, v139, v171
	v_add_f32_e32 v168, v141, v239
	v_med3_f32 v170, v170, s85, v226
	v_med3_f32 v171, v171, s85, v226
	v_med3_f32 v180, v180, s85, v226
	v_med3_f32 v168, v168, s85, v226
	v_mul_f32_e32 v170, 0xbfb8aa3b, v170
	v_mul_f32_e32 v171, 0xbfb8aa3b, v171
	v_mul_f32_e32 v180, 0xbfb8aa3b, v180
	v_mul_f32_e32 v168, 0xbfb8aa3b, v168
	v_exp_f32_e32 v170, v170
	v_exp_f32_e32 v171, v171
	v_add_f32_e32 v173, 1.0, v173
	v_exp_f32_e32 v180, v180
	v_exp_f32_e32 v181, v168
	v_pk_mul_f32 v[106:107], v[106:107], v[166:167]
	v_add_f32_e32 v166, 1.0, v169
	v_rcp_f32_e32 v173, v173
	v_rcp_f32_e32 v239, v166
	v_pk_add_f32 v[166:167], v[180:181], 1.0 op_sel_hi:[1,0]
	v_pk_add_f32 v[168:169], v[170:171], 1.0 op_sel_hi:[1,0]
	v_pk_mul_f32 v[166:167], v[238:239], v[166:167]
	v_pk_mul_f32 v[168:169], v[172:173], v[168:169]
	v_pk_mul_f32 v[104:105], v[104:105], v[166:167]
	v_pk_mul_f32 v[102:103], v[102:103], v[168:169]
	global_load_dwordx4 v[174:177], v[178:179], off offset:2048
	s_nop 0
	global_load_dwordx4 v[178:181], v[178:179], off offset:3072
	s_nop 0
	global_load_dwordx4 v[166:169], v[236:237], off offset:2048
	global_load_dwordx4 v[170:173], v[236:237], off offset:3072
	s_waitcnt vmcnt(7)
	ds_write_b128 v3, v[190:193]
	s_waitcnt vmcnt(6)
	ds_write_b128 v3, v[194:197] offset:1152
	ds_read_b128 v[190:193], v188
	ds_read_b128 v[194:197], v188 offset:64
	s_waitcnt vmcnt(5)
	ds_write_b128 v3, v[228:231]
	s_waitcnt vmcnt(4)
	ds_write_b128 v3, v[232:235] offset:1152
	v_and_b32_e32 v247, 63, v218
	v_lshlrev_b32_e32 v247, 7, v247
	v_lshl_or_b32 v247, v247, 7, v247
	v_and_b32_e32 v247, 0x80f80, v247
	s_add_u32 s90, s90, 0x3000
	s_addc_u32 s91, s91, 0
	global_load_dword v247, v247, s[90:91]
	ds_read_b128 v[228:231], v188
	ds_read_b128 v[232:235], v188 offset:64
	s_waitcnt lgkmcnt(5)
	v_lshlrev_b32_e32 v189, 16, v190
	v_add_f32_e32 v189, v158, v189
	v_med3_f32 v189, v189, s85, v226
	v_mul_f32_e32 v189, 0xbfb8aa3b, v189
	v_lshlrev_b32_e32 v236, 16, v191
	v_and_b32_e32 v237, 0xffff0000, v191
	v_lshlrev_b32_e32 v191, 16, v192
	v_exp_f32_e32 v189, v189
	v_add_f32_e32 v191, v150, v191
	v_med3_f32 v191, v191, s85, v226
	v_mul_f32_e32 v191, 0xbfb8aa3b, v191
	v_and_b32_e32 v227, 0xffff0000, v190
	v_lshlrev_b32_e32 v239, 16, v193
	v_and_b32_e32 v241, 0xffff0000, v193
	s_waitcnt lgkmcnt(1)
; #define UNPK0(q_) ((f32x4){bf_lo((q_).x), bf_hi((q_).x), bf_lo((q_).y), bf_hi((q_).y)})
; #define UNPK1(q_) ((f32x4){bf_lo((q_).z), bf_hi((q_).z), bf_lo((q_).w), bf_hi((q_).w)})
;     static __device__ __forceinline__ float eneg(float g) { return __builtin_amdgcn_exp2f(-1.4426950408889634f * fminf(fmaxf(g, -30.f), 30.f)); }
;     __device__ __forceinline__ void mid(f32x4 (&acc)[2][2][4][2], const Unit& u, int wr, int wc, int fr, int fq) const {
;     ...
;                 for (int bj = 0; bj < 2; ++bj) { const u32x4 ga = bj ? ga1 : ga0, gb = bj ? gb1 : gb0;
;                     const f32x4 a0 = UNPK0(ga) + ba[bj][0], a1 = UNPK1(ga) + ba[bj][1], b0 = UNPK0(gb) + bb[bj][0], b1 = UNPK1(gb) + bb[bj][1];
; #pragma unroll
;                     for (int k = 0; k < 4; ++k) { acc[ai][bj][m][0][k] *= (1.0f + eneg(b0[k])) * __builtin_amdgcn_rcpf(1.0f + eneg(a0[k]));
;                                                   acc[ai][bj][m][1][k] *= (1.0f + eneg(b1[k])) * __builtin_amdgcn_rcpf(1.0f + eneg(a1[k])); } } }
	v_lshlrev_b32_e32 v190, 16, v228
	v_and_b32_e32 v193, 0xffff0000, v228
	v_lshlrev_b32_e32 v228, 16, v230
	v_add_f32_e32 v189, 1.0, v189
	v_exp_f32_e32 v191, v191
	v_and_b32_e32 v238, 0xffff0000, v192
	v_rcp_f32_e32 v192, v189
	v_add_f32_e32 v189, v154, v228
	v_med3_f32 v189, v189, s85, v226
	v_mul_f32_e32 v189, 0xbfb8aa3b, v189
	v_exp_f32_e32 v228, v189
	v_add_f32_e32 v189, 1.0, v191
	v_add_f32_e32 v191, v159, v227
	v_med3_f32 v191, v191, s85, v226
	v_mul_f32_e32 v191, 0xbfb8aa3b, v191
	v_lshlrev_b32_e32 v240, 16, v229
	v_and_b32_e32 v242, 0xffff0000, v229
	v_and_b32_e32 v229, 0xffff0000, v230
	v_rcp_f32_e32 v230, v189
	v_add_f32_e32 v189, v163, v193
	v_exp_f32_e32 v193, v191
	v_add_f32_e32 v227, v151, v238
	v_med3_f32 v189, v189, s85, v226
	v_med3_f32 v227, v227, s85, v226
	v_mul_f32_e32 v189, 0xbfb8aa3b, v189
	v_mul_f32_e32 v227, 0xbfb8aa3b, v227
	v_exp_f32_e32 v191, v189
	v_add_f32_e32 v189, 1.0, v193
	v_exp_f32_e32 v227, v227
	v_rcp_f32_e32 v193, v189
	v_add_f32_e32 v189, v155, v229
	v_med3_f32 v189, v189, s85, v226
	v_mul_f32_e32 v189, 0xbfb8aa3b, v189
	v_exp_f32_e32 v229, v189
	v_add_f32_e32 v189, 1.0, v227
	v_add_f32_e32 v227, v160, v236
	v_med3_f32 v227, v227, s85, v226
	v_mul_f32_e32 v227, 0xbfb8aa3b, v227
	v_exp_f32_e32 v227, v227
	v_lshlrev_b32_e32 v243, 16, v231
	v_and_b32_e32 v244, 0xffff0000, v231
	v_rcp_f32_e32 v231, v189
	v_add_f32_e32 v189, v164, v240
	v_med3_f32 v189, v189, s85, v226
	v_mul_f32_e32 v189, 0xbfb8aa3b, v189
	v_exp_f32_e32 v236, v189
	v_add_f32_e32 v189, 1.0, v227
	v_add_f32_e32 v227, v152, v239
	v_med3_f32 v227, v227, s85, v226
	v_mul_f32_e32 v227, 0xbfb8aa3b, v227
	v_exp_f32_e32 v227, v227
	v_add_f32_e32 v237, v161, v237
	v_rcp_f32_e32 v238, v189
	v_add_f32_e32 v189, v156, v243
	v_med3_f32 v237, v237, s85, v226
	v_med3_f32 v189, v189, s85, v226
	v_mul_f32_e32 v237, 0xbfb8aa3b, v237
	v_mul_f32_e32 v189, 0xbfb8aa3b, v189
	v_exp_f32_e32 v239, v237
	v_add_f32_e32 v190, v162, v190
	v_exp_f32_e32 v240, v189
	v_add_f32_e32 v189, 1.0, v227
	v_add_f32_e32 v227, v165, v242
	v_med3_f32 v190, v190, s85, v226
	v_med3_f32 v227, v227, s85, v226
	v_mul_f32_e32 v190, 0xbfb8aa3b, v190
	v_mul_f32_e32 v227, 0xbfb8aa3b, v227
	v_exp_f32_e32 v190, v190
	v_exp_f32_e32 v237, v227
	v_rcp_f32_e32 v242, v189
	v_add_f32_e32 v189, 1.0, v239
	v_rcp_f32_e32 v239, v189
	v_pk_add_f32 v[236:237], v[236:237], 1.0 op_sel_hi:[1,0]
	v_pk_add_f32 v[190:191], v[190:191], 1.0 op_sel_hi:[1,0]
	v_add_f32_e32 v189, v157, v244
	v_pk_mul_f32 v[190:191], v[192:193], v[190:191]
	v_pk_mul_f32 v[192:193], v[238:239], v[236:237]
	v_med3_f32 v189, v189, s85, v226
	v_pk_mul_f32 v[100:101], v[100:101], v[192:193]
	v_add_f32_e32 v192, v153, v241
	v_med3_f32 v192, v192, s85, v226
	v_mul_f32_e32 v192, 0xbfb8aa3b, v192
	v_exp_f32_e32 v192, v192
	v_mul_f32_e32 v189, 0xbfb8aa3b, v189
	v_exp_f32_e32 v241, v189
	v_pk_mul_f32 v[98:99], v[98:99], v[190:191]
	v_add_f32_e32 v189, 1.0, v192
	v_rcp_f32_e32 v243, v189
	v_lshlrev_b32_e32 v189, 16, v194
	v_add_f32_e32 v189, v142, v189
	v_pk_add_f32 v[192:193], v[228:229], 1.0 op_sel_hi:[1,0]
	v_med3_f32 v189, v189, s85, v226
	v_pk_mul_f32 v[192:193], v[230:231], v[192:193]
	v_mul_f32_e32 v189, 0xbfb8aa3b, v189
	v_pk_mul_f32 v[94:95], v[94:95], v[192:193]
	v_lshlrev_b32_e32 v193, 16, v196
	v_exp_f32_e32 v189, v189
	v_add_f32_e32 v193, v134, v193
	v_pk_add_f32 v[190:191], v[240:241], 1.0 op_sel_hi:[1,0]
	v_med3_f32 v193, v193, s85, v226
	v_pk_mul_f32 v[190:191], v[242:243], v[190:191]
	v_mul_f32_e32 v193, 0xbfb8aa3b, v193
	v_pk_mul_f32 v[96:97], v[96:97], v[190:191]
	v_and_b32_e32 v191, 0xffff0000, v194
	s_waitcnt lgkmcnt(0)
	v_lshlrev_b32_e32 v194, 16, v234
	v_add_f32_e32 v189, 1.0, v189
	v_exp_f32_e32 v193, v193
	v_rcp_f32_e32 v192, v189
	v_add_f32_e32 v189, v138, v194
	v_add_f32_e32 v191, v143, v191
	v_med3_f32 v189, v189, s85, v226
	v_med3_f32 v191, v191, s85, v226
	v_mul_f32_e32 v189, 0xbfb8aa3b, v189
	v_mul_f32_e32 v191, 0xbfb8aa3b, v191
	v_lshlrev_b32_e32 v227, 16, v195
	v_and_b32_e32 v229, 0xffff0000, v195
	v_and_b32_e32 v195, 0xffff0000, v196
	v_lshlrev_b32_e32 v231, 16, v197
	v_and_b32_e32 v236, 0xffff0000, v197
	v_and_b32_e32 v197, 0xffff0000, v232
	v_exp_f32_e32 v194, v189
	v_add_f32_e32 v189, 1.0, v193
	v_exp_f32_e32 v193, v191
	v_rcp_f32_e32 v196, v189
	v_add_f32_e32 v189, v147, v197
	v_add_f32_e32 v195, v135, v195
	v_med3_f32 v189, v189, s85, v226
	v_med3_f32 v195, v195, s85, v226
	v_mul_f32_e32 v189, 0xbfb8aa3b, v189
	v_mul_f32_e32 v195, 0xbfb8aa3b, v195
	v_and_b32_e32 v230, 0xffff0000, v234
	v_exp_f32_e32 v191, v189
	v_add_f32_e32 v189, 1.0, v193
	v_exp_f32_e32 v197, v195
	v_rcp_f32_e32 v193, v189
	v_add_f32_e32 v189, v139, v230
	v_add_f32_e32 v227, v144, v227
	v_med3_f32 v189, v189, s85, v226
	v_med3_f32 v227, v227, s85, v226
	v_mul_f32_e32 v189, 0xbfb8aa3b, v189
	v_mul_f32_e32 v227, 0xbfb8aa3b, v227
	v_lshlrev_b32_e32 v228, 16, v233
	v_exp_f32_e32 v195, v189
	v_add_f32_e32 v189, 1.0, v197
	v_exp_f32_e32 v227, v227
	v_rcp_f32_e32 v197, v189
	v_add_f32_e32 v189, v148, v228
	v_med3_f32 v189, v189, s85, v226
	v_mul_f32_e32 v189, 0xbfb8aa3b, v189
	v_exp_f32_e32 v228, v189
	v_add_f32_e32 v189, 1.0, v227
	v_add_f32_e32 v227, v136, v231
	v_med3_f32 v227, v227, s85, v226
	v_mul_f32_e32 v227, 0xbfb8aa3b, v227
	v_lshlrev_b32_e32 v190, 16, v232
	v_lshlrev_b32_e32 v232, 16, v235
	v_exp_f32_e32 v227, v227
	v_add_f32_e32 v229, v145, v229
	v_rcp_f32_e32 v230, v189
	v_add_f32_e32 v189, v140, v232
	v_med3_f32 v229, v229, s85, v226
	v_med3_f32 v189, v189, s85, v226
	v_mul_f32_e32 v229, 0xbfb8aa3b, v229
	v_and_b32_e32 v233, 0xffff0000, v233
	v_mul_f32_e32 v189, 0xbfb8aa3b, v189
	v_exp_f32_e32 v231, v229
	v_add_f32_e32 v190, v146, v190
	v_exp_f32_e32 v232, v189
	v_add_f32_e32 v189, 1.0, v227
	v_add_f32_e32 v227, v149, v233
	v_med3_f32 v190, v190, s85, v226
	v_med3_f32 v227, v227, s85, v226
	v_mul_f32_e32 v190, 0xbfb8aa3b, v190
	v_mul_f32_e32 v227, 0xbfb8aa3b, v227
	v_exp_f32_e32 v190, v190
	v_exp_f32_e32 v229, v227
	v_rcp_f32_e32 v234, v189
	v_add_f32_e32 v189, 1.0, v231
	v_rcp_f32_e32 v231, v189
	v_pk_add_f32 v[228:229], v[228:229], 1.0 op_sel_hi:[1,0]
	v_pk_add_f32 v[190:191], v[190:191], 1.0 op_sel_hi:[1,0]
	v_and_b32_e32 v235, 0xffff0000, v235
	v_pk_mul_f32 v[190:191], v[192:193], v[190:191]
	v_pk_mul_f32 v[192:193], v[230:231], v[228:229]
	v_add_f32_e32 v189, v141, v235
	v_pk_mul_f32 v[92:93], v[92:93], v[192:193]
	v_add_f32_e32 v192, v137, v236
	v_med3_f32 v192, v192, s85, v226
	v_mul_f32_e32 v192, 0xbfb8aa3b, v192
	v_exp_f32_e32 v192, v192
	v_med3_f32 v189, v189, s85, v226
	v_mul_f32_e32 v189, 0xbfb8aa3b, v189
	v_exp_f32_e32 v233, v189
	v_add_f32_e32 v189, 1.0, v192
	v_rcp_f32_e32 v235, v189
	s_waitcnt vmcnt(4)
; #define UNPK0(q_) ((f32x4){bf_lo((q_).x), bf_hi((q_).x), bf_lo((q_).y), bf_hi((q_).y)})
; #define UNPK1(q_) ((f32x4){bf_lo((q_).z), bf_hi((q_).z), bf_lo((q_).w), bf_hi((q_).w)})
;     static __device__ __forceinline__ float eneg(float g) { return __builtin_amdgcn_exp2f(-1.4426950408889634f * fminf(fmaxf(g, -30.f), 30.f)); }
;     __device__ __forceinline__ void mid(f32x4 (&acc)[2][2][4][2], const Unit& u, int wr, int wc, int fr, int fq) const {
;     ...
;             for (int m = 2 * (am & 1); m < 2 * (am & 1) + 2; ++m) {
;                 pa.stage(ra[m][0], ra[m][1]); const u32x4 ga0 = pa.get(0), ga1 = pa.get(1);
;                 asm volatile("" ::: "memory");
;                 pb.stage(rb[m][0], rb[m][1]); const u32x4 gb0 = pb.get(0), gb1 = pb.get(1);
;                 asm volatile("" ::: "memory");
; #pragma unroll
;                 for (int bj = 0; bj < 2; ++bj) { const u32x4 ga = bj ? ga1 : ga0, gb = bj ? gb1 : gb0;
;                     const f32x4 a0 = UNPK0(ga) + ba[bj][0], a1 = UNPK1(ga) + ba[bj][1], b0 = UNPK0(gb) + bb[bj][0], b1 = UNPK1(gb) + bb[bj][1];
; #pragma unroll
;                     for (int k = 0; k < 4; ++k) { acc[ai][bj][m][0][k] *= (1.0f + eneg(b0[k])) * __builtin_amdgcn_rcpf(1.0f + eneg(a0[k]));
;                                                   acc[ai][bj][m][1][k] *= (1.0f + eneg(b1[k])) * __builtin_amdgcn_rcpf(1.0f + eneg(a1[k])); } } }
	ds_write_b128 v3, v[174:177]
	s_waitcnt vmcnt(3)
	ds_write_b128 v3, v[178:181] offset:1152
	ds_read_b128 v[174:177], v188
	ds_read_b128 v[178:181], v188 offset:64
	s_waitcnt vmcnt(2)
	ds_write_b128 v3, v[166:169]
	s_waitcnt vmcnt(1)
	ds_write_b128 v3, v[170:173] offset:1152
	ds_read_b128 v[166:169], v188
	ds_read_b128 v[170:173], v188 offset:64
	v_pk_mul_f32 v[90:91], v[90:91], v[190:191]
	v_pk_add_f32 v[190:191], v[232:233], 1.0 op_sel_hi:[1,0]
	s_waitcnt lgkmcnt(5)
	v_lshlrev_b32_e32 v189, 16, v174
	v_pk_mul_f32 v[190:191], v[234:235], v[190:191]
	s_waitcnt lgkmcnt(1)
	v_lshlrev_b32_e32 v227, 16, v169
	v_pk_mul_f32 v[88:89], v[88:89], v[190:191]
	v_and_b32_e32 v190, 0xffff0000, v174
	v_lshlrev_b32_e32 v174, 16, v176
	v_and_b32_e32 v228, 0xffff0000, v169
	v_add_f32_e32 v169, v150, v174
	v_pk_add_f32 v[192:193], v[194:195], 1.0 op_sel_hi:[1,0]
	v_med3_f32 v169, v169, s85, v226
	v_pk_mul_f32 v[192:193], v[196:197], v[192:193]
	v_mul_f32_e32 v169, 0xbfb8aa3b, v169
	v_pk_mul_f32 v[86:87], v[86:87], v[192:193]
	v_lshlrev_b32_e32 v191, 16, v175
	v_and_b32_e32 v193, 0xffff0000, v175
	v_and_b32_e32 v175, 0xffff0000, v176
	v_lshlrev_b32_e32 v192, 16, v167
	v_and_b32_e32 v196, 0xffff0000, v167
	v_lshlrev_b32_e32 v167, 16, v168
	v_exp_f32_e32 v169, v169
	v_add_f32_e32 v167, v154, v167
	v_add_f32_e32 v175, v151, v175
	v_med3_f32 v167, v167, s85, v226
	v_med3_f32 v175, v175, s85, v226
	v_mul_f32_e32 v167, 0xbfb8aa3b, v167
	v_mul_f32_e32 v175, 0xbfb8aa3b, v175
	v_and_b32_e32 v197, 0xffff0000, v168
	v_add_f32_e32 v168, v158, v189
	v_exp_f32_e32 v174, v167
	v_add_f32_e32 v167, 1.0, v169
	v_add_f32_e32 v169, v159, v190
	v_exp_f32_e32 v189, v175
	v_add_f32_e32 v190, v160, v191
	v_med3_f32 v190, v190, s85, v226
	v_lshlrev_b32_e32 v194, 16, v177
	v_and_b32_e32 v195, 0xffff0000, v177
	v_lshlrev_b32_e32 v176, 16, v166
	v_and_b32_e32 v177, 0xffff0000, v166
	v_mul_f32_e32 v190, 0xbfb8aa3b, v190
	v_add_f32_e32 v166, v162, v176
	v_rcp_f32_e32 v176, v167
	v_add_f32_e32 v167, v163, v177
	v_add_f32_e32 v177, v155, v197
	v_exp_f32_e32 v191, v190
	v_med3_f32 v175, v177, s85, v226
	v_add_f32_e32 v177, 1.0, v189
	v_add_f32_e32 v189, v164, v192
	v_med3_f32 v189, v189, s85, v226
	v_mul_f32_e32 v189, 0xbfb8aa3b, v189
	v_exp_f32_e32 v190, v189
	v_add_f32_e32 v189, 1.0, v191
	v_add_f32_e32 v191, v152, v194
	v_med3_f32 v191, v191, s85, v226
	v_mul_f32_e32 v191, 0xbfb8aa3b, v191
	v_exp_f32_e32 v191, v191
	v_add_f32_e32 v193, v161, v193
	v_med3_f32 v168, v168, s85, v226
	v_med3_f32 v169, v169, s85, v226
	v_rcp_f32_e32 v192, v189
	v_add_f32_e32 v189, v156, v227
	v_med3_f32 v193, v193, s85, v226
	v_mul_f32_e32 v168, 0xbfb8aa3b, v168
	v_mul_f32_e32 v169, 0xbfb8aa3b, v169
	v_med3_f32 v189, v189, s85, v226
	v_mul_f32_e32 v193, 0xbfb8aa3b, v193
	v_exp_f32_e32 v168, v168
	v_exp_f32_e32 v169, v169
	v_mul_f32_e32 v189, 0xbfb8aa3b, v189
	v_exp_f32_e32 v193, v193
	v_exp_f32_e32 v194, v189
	v_add_f32_e32 v189, 1.0, v191
	v_add_f32_e32 v191, v165, v196
	v_med3_f32 v166, v166, s85, v226
	v_med3_f32 v167, v167, s85, v226
	v_med3_f32 v191, v191, s85, v226
	v_mul_f32_e32 v166, 0xbfb8aa3b, v166
	v_mul_f32_e32 v167, 0xbfb8aa3b, v167
	v_mul_f32_e32 v191, 0xbfb8aa3b, v191
	v_exp_f32_e32 v166, v166
	v_add_f32_e32 v168, 1.0, v168
	v_exp_f32_e32 v167, v167
	v_add_f32_e32 v169, 1.0, v169
	v_exp_f32_e32 v191, v191
	v_rcp_f32_e32 v196, v189
	v_add_f32_e32 v189, 1.0, v193
	v_rcp_f32_e32 v168, v168
	v_rcp_f32_e32 v169, v169
	v_rcp_f32_e32 v193, v189
	v_pk_add_f32 v[190:191], v[190:191], 1.0 op_sel_hi:[1,0]
	v_pk_add_f32 v[166:167], v[166:167], 1.0 op_sel_hi:[1,0]
	v_mul_f32_e32 v175, 0xbfb8aa3b, v175
	v_pk_mul_f32 v[166:167], v[168:169], v[166:167]
	v_pk_mul_f32 v[168:169], v[192:193], v[190:191]
	v_exp_f32_e32 v175, v175
	v_pk_mul_f32 v[84:85], v[84:85], v[168:169]
	v_add_f32_e32 v169, v153, v195
	v_med3_f32 v169, v169, s85, v226
	v_mul_f32_e32 v169, 0xbfb8aa3b, v169
	v_exp_f32_e32 v169, v169
	v_add_f32_e32 v168, v157, v228
	v_med3_f32 v168, v168, s85, v226
	v_mul_f32_e32 v168, 0xbfb8aa3b, v168
	v_rcp_f32_e32 v177, v177
	v_exp_f32_e32 v195, v168
	v_pk_mul_f32 v[82:83], v[82:83], v[166:167]
	v_add_f32_e32 v166, 1.0, v169
	v_rcp_f32_e32 v197, v166
	v_pk_add_f32 v[168:169], v[174:175], 1.0 op_sel_hi:[1,0]
	v_pk_add_f32 v[166:167], v[194:195], 1.0 op_sel_hi:[1,0]
	v_pk_mul_f32 v[168:169], v[176:177], v[168:169]
	v_pk_mul_f32 v[166:167], v[196:197], v[166:167]
	v_pk_mul_f32 v[78:79], v[78:79], v[168:169]
	v_lshlrev_b32_e32 v169, 16, v180
	v_pk_mul_f32 v[80:81], v[80:81], v[166:167]
	v_lshlrev_b32_e32 v166, 16, v178
	v_add_f32_e32 v169, v134, v169
	v_add_f32_e32 v166, v142, v166
	v_med3_f32 v169, v169, s85, v226
	v_med3_f32 v166, v166, s85, v226
	v_mul_f32_e32 v169, 0xbfb8aa3b, v169
	v_mul_f32_e32 v166, 0xbfb8aa3b, v166
	v_exp_f32_e32 v169, v169
	v_and_b32_e32 v167, 0xffff0000, v178
	v_and_b32_e32 v176, 0xffff0000, v180
	s_waitcnt lgkmcnt(0)
; #define UNPK0(q_) ((f32x4){bf_lo((q_).x), bf_hi((q_).x), bf_lo((q_).y), bf_hi((q_).y)})
; #define UNPK1(q_) ((f32x4){bf_lo((q_).z), bf_hi((q_).z), bf_lo((q_).w), bf_hi((q_).w)})
;     static __device__ __forceinline__ float eneg(float g) { return __builtin_amdgcn_exp2f(-1.4426950408889634f * fminf(fmaxf(g, -30.f), 30.f)); }
;     __device__ __forceinline__ void mid(f32x4 (&acc)[2][2][4][2], const Unit& u, int wr, int wc, int fr, int fq) const {
;     ...
;         for (int am = 0; am < 4; ++am) { const int ai = am >> 1;
;             u32x4 ra[4][2], rb[4][2];
; #pragma unroll
;             for (int m = 2 * (am & 1); m < 2 * (am & 1) + 2; ++m) { pa.fetch(ai, m, ra[m][0], ra[m][1]); pb.fetch(ai, m, rb[m][0], rb[m][1]); }
;             asm volatile("" ::: "memory");
; #pragma unroll
;             for (int m = 2 * (am & 1); m < 2 * (am & 1) + 2; ++m) {
;                 pa.stage(ra[m][0], ra[m][1]); const u32x4 ga0 = pa.get(0), ga1 = pa.get(1);
;                 asm volatile("" ::: "memory");
;                 pb.stage(rb[m][0], rb[m][1]); const u32x4 gb0 = pb.get(0), gb1 = pb.get(1);
;                 asm volatile("" ::: "memory");
; #pragma unroll
;                 for (int bj = 0; bj < 2; ++bj) { const u32x4 ga = bj ? ga1 : ga0, gb = bj ? gb1 : gb0;
;                     const f32x4 a0 = UNPK0(ga) + ba[bj][0], a1 = UNPK1(ga) + ba[bj][1], b0 = UNPK0(gb) + bb[bj][0], b1 = UNPK1(gb) + bb[bj][1];
; #pragma unroll
;                     for (int k = 0; k < 4; ++k) { acc[ai][bj][m][0][k] *= (1.0f + eneg(b0[k])) * __builtin_amdgcn_rcpf(1.0f + eneg(a0[k]));
;                                                   acc[ai][bj][m][1][k] *= (1.0f + eneg(b1[k])) * __builtin_amdgcn_rcpf(1.0f + eneg(a1[k])); } } }
	v_lshlrev_b32_e32 v168, 16, v170
	v_and_b32_e32 v178, 0xffff0000, v170
	v_lshlrev_b32_e32 v180, 16, v171
	v_and_b32_e32 v189, 0xffff0000, v171
	v_lshlrev_b32_e32 v170, 16, v172
	v_and_b32_e32 v171, 0xffff0000, v172
	v_exp_f32_e32 v172, v166
	v_add_f32_e32 v168, v146, v168
	v_add_f32_e32 v169, 1.0, v169
	v_med3_f32 v166, v168, s85, v226
	v_add_f32_e32 v168, 1.0, v172
	v_rcp_f32_e32 v172, v169
	v_add_f32_e32 v169, v147, v178
	v_add_co_u32_e32 v178, vcc, s79, v186
	v_lshlrev_b32_e32 v174, 16, v179
	v_and_b32_e32 v175, 0xffff0000, v179
	v_addc_co_u32_e32 v179, vcc, 0, v187, vcc
	v_add_co_u32_e32 v186, vcc, s86, v186
	v_add_f32_e32 v167, v143, v167
	s_nop 0
	v_addc_co_u32_e32 v187, vcc, 0, v187, vcc
	global_load_dwordx4 v[190:193], v[186:187], off offset:-4096
	global_load_dwordx4 v[194:197], v[178:179], off offset:1024
	v_add_co_u32_e32 v236, vcc, s79, v4
	v_med3_f32 v167, v167, s85, v226
	s_nop 0
	v_addc_co_u32_e32 v237, vcc, 0, v5, vcc
	v_add_co_u32_e32 v4, vcc, s86, v4
	v_mul_f32_e32 v167, 0xbfb8aa3b, v167
	s_nop 0
	v_addc_co_u32_e32 v5, vcc, 0, v5, vcc
	global_load_dwordx4 v[228:231], v[4:5], off offset:-4096
	global_load_dwordx4 v[232:235], v[236:237], off offset:1024
	v_lshlrev_b32_e32 v227, 16, v173
	v_and_b32_e32 v239, 0xffff0000, v173
	v_exp_f32_e32 v173, v167
	v_add_f32_e32 v174, v144, v174
	v_med3_f32 v174, v174, s85, v226
	v_lshlrev_b32_e32 v177, 16, v181
	v_mul_f32_e32 v174, 0xbfb8aa3b, v174
	v_med3_f32 v167, v169, s85, v226
	v_add_f32_e32 v169, 1.0, v173
	v_add_f32_e32 v173, v135, v176
	v_add_f32_e32 v176, v148, v180
	v_exp_f32_e32 v180, v174
	v_add_f32_e32 v177, v136, v177
	v_med3_f32 v177, v177, s85, v226
	v_add_f32_e32 v175, v145, v175
	v_mul_f32_e32 v177, 0xbfb8aa3b, v177
	v_med3_f32 v175, v175, s85, v226
	v_exp_f32_e32 v177, v177
	v_mul_f32_e32 v175, 0xbfb8aa3b, v175
	v_med3_f32 v174, v176, s85, v226
	v_add_f32_e32 v176, 1.0, v180
	v_add_f32_e32 v180, v140, v227
	v_exp_f32_e32 v227, v175
	v_add_f32_e32 v189, v149, v189
	v_med3_f32 v189, v189, s85, v226
	v_mul_f32_e32 v166, 0xbfb8aa3b, v166
	v_mul_f32_e32 v167, 0xbfb8aa3b, v167
	v_mul_f32_e32 v174, 0xbfb8aa3b, v174
	v_add_f32_e32 v177, 1.0, v177
	v_mul_f32_e32 v175, 0xbfb8aa3b, v189
	v_exp_f32_e32 v166, v166
	v_exp_f32_e32 v167, v167
	v_exp_f32_e32 v174, v174
	v_exp_f32_e32 v175, v175
	v_rcp_f32_e32 v238, v177
	v_add_f32_e32 v177, 1.0, v227
	v_rcp_f32_e32 v168, v168
	v_rcp_f32_e32 v169, v169
	v_rcp_f32_e32 v176, v176
	v_rcp_f32_e32 v177, v177
	v_pk_add_f32 v[174:175], v[174:175], 1.0 op_sel_hi:[1,0]
	v_pk_add_f32 v[166:167], v[166:167], 1.0 op_sel_hi:[1,0]
	v_and_b32_e32 v181, 0xffff0000, v181
	v_pk_mul_f32 v[166:167], v[168:169], v[166:167]
	v_pk_mul_f32 v[168:169], v[176:177], v[174:175]
	v_med3_f32 v173, v173, s85, v226
	v_pk_mul_f32 v[76:77], v[76:77], v[168:169]
	v_add_f32_e32 v169, v137, v181
	v_med3_f32 v169, v169, s85, v226
	v_mul_f32_e32 v173, 0xbfb8aa3b, v173
	v_mul_f32_e32 v169, 0xbfb8aa3b, v169
	v_exp_f32_e32 v173, v173
	v_exp_f32_e32 v169, v169
	v_add_f32_e32 v170, v138, v170
	v_add_f32_e32 v171, v139, v171
	v_add_f32_e32 v168, v141, v239
	v_med3_f32 v170, v170, s85, v226
	v_med3_f32 v171, v171, s85, v226
	v_med3_f32 v180, v180, s85, v226
	v_med3_f32 v168, v168, s85, v226
	v_mul_f32_e32 v170, 0xbfb8aa3b, v170
	v_mul_f32_e32 v171, 0xbfb8aa3b, v171
	v_mul_f32_e32 v180, 0xbfb8aa3b, v180
	v_mul_f32_e32 v168, 0xbfb8aa3b, v168
	v_exp_f32_e32 v170, v170
	v_exp_f32_e32 v171, v171
	v_add_f32_e32 v173, 1.0, v173
	v_exp_f32_e32 v180, v180
	v_exp_f32_e32 v181, v168
	v_pk_mul_f32 v[74:75], v[74:75], v[166:167]
	v_add_f32_e32 v166, 1.0, v169
	v_rcp_f32_e32 v173, v173
	v_rcp_f32_e32 v239, v166
	v_pk_add_f32 v[166:167], v[180:181], 1.0 op_sel_hi:[1,0]
	v_pk_add_f32 v[168:169], v[170:171], 1.0 op_sel_hi:[1,0]
	v_pk_mul_f32 v[166:167], v[238:239], v[166:167]
	v_pk_mul_f32 v[168:169], v[172:173], v[168:169]
	v_pk_mul_f32 v[72:73], v[72:73], v[166:167]
	v_pk_mul_f32 v[70:71], v[70:71], v[168:169]
	global_load_dwordx4 v[174:177], v[178:179], off offset:2048
	s_nop 0
	global_load_dwordx4 v[178:181], v[178:179], off offset:3072
	s_nop 0
	global_load_dwordx4 v[166:169], v[236:237], off offset:2048
	global_load_dwordx4 v[170:173], v[236:237], off offset:3072
	s_waitcnt vmcnt(7)
	ds_write_b128 v3, v[190:193]
	s_waitcnt vmcnt(6)
	ds_write_b128 v3, v[194:197] offset:1152
	ds_read_b128 v[190:193], v188
	ds_read_b128 v[194:197], v188 offset:64
	s_waitcnt vmcnt(5)
	ds_write_b128 v3, v[228:231]
	s_waitcnt vmcnt(4)
	ds_write_b128 v3, v[232:235] offset:1152
	v_and_b32_e32 v247, 63, v218
	v_lshlrev_b32_e32 v247, 7, v247
	v_lshl_or_b32 v247, v247, 7, v247
	v_and_b32_e32 v247, 0x80f80, v247
	s_add_u32 s90, s90, 0x1000
	s_addc_u32 s91, s91, 0
	global_load_dword v247, v247, s[90:91]
	ds_read_b128 v[228:231], v188
	ds_read_b128 v[232:235], v188 offset:64
	s_waitcnt lgkmcnt(5)
	v_lshlrev_b32_e32 v189, 16, v190
	v_add_f32_e32 v189, v158, v189
	v_med3_f32 v189, v189, s85, v226
	v_mul_f32_e32 v189, 0xbfb8aa3b, v189
	v_lshlrev_b32_e32 v236, 16, v191
	v_and_b32_e32 v237, 0xffff0000, v191
	v_lshlrev_b32_e32 v191, 16, v192
	v_exp_f32_e32 v189, v189
	v_add_f32_e32 v191, v150, v191
	v_med3_f32 v191, v191, s85, v226
	v_mul_f32_e32 v191, 0xbfb8aa3b, v191
	v_and_b32_e32 v227, 0xffff0000, v190
	v_lshlrev_b32_e32 v239, 16, v193
	v_and_b32_e32 v241, 0xffff0000, v193
	s_waitcnt lgkmcnt(1)
; #define UNPK0(q_) ((f32x4){bf_lo((q_).x), bf_hi((q_).x), bf_lo((q_).y), bf_hi((q_).y)})
; #define UNPK1(q_) ((f32x4){bf_lo((q_).z), bf_hi((q_).z), bf_lo((q_).w), bf_hi((q_).w)})
;     static __device__ __forceinline__ float eneg(float g) { return __builtin_amdgcn_exp2f(-1.4426950408889634f * fminf(fmaxf(g, -30.f), 30.f)); }
;     __device__ __forceinline__ void mid(f32x4 (&acc)[2][2][4][2], const Unit& u, int wr, int wc, int fr, int fq) const {
;     ...
;                 for (int bj = 0; bj < 2; ++bj) { const u32x4 ga = bj ? ga1 : ga0, gb = bj ? gb1 : gb0;
;                     const f32x4 a0 = UNPK0(ga) + ba[bj][0], a1 = UNPK1(ga) + ba[bj][1], b0 = UNPK0(gb) + bb[bj][0], b1 = UNPK1(gb) + bb[bj][1];
; #pragma unroll
;                     for (int k = 0; k < 4; ++k) { acc[ai][bj][m][0][k] *= (1.0f + eneg(b0[k])) * __builtin_amdgcn_rcpf(1.0f + eneg(a0[k]));
;                                                   acc[ai][bj][m][1][k] *= (1.0f + eneg(b1[k])) * __builtin_amdgcn_rcpf(1.0f + eneg(a1[k])); } } }
	v_lshlrev_b32_e32 v190, 16, v228
	v_and_b32_e32 v193, 0xffff0000, v228
	v_lshlrev_b32_e32 v228, 16, v230
	v_add_f32_e32 v189, 1.0, v189
	v_exp_f32_e32 v191, v191
	v_and_b32_e32 v238, 0xffff0000, v192
	v_rcp_f32_e32 v192, v189
	v_add_f32_e32 v189, v154, v228
	v_med3_f32 v189, v189, s85, v226
	v_mul_f32_e32 v189, 0xbfb8aa3b, v189
	v_exp_f32_e32 v228, v189
	v_add_f32_e32 v189, 1.0, v191
	v_add_f32_e32 v191, v159, v227
	v_med3_f32 v191, v191, s85, v226
	v_mul_f32_e32 v191, 0xbfb8aa3b, v191
	v_lshlrev_b32_e32 v240, 16, v229
	v_and_b32_e32 v242, 0xffff0000, v229
	v_and_b32_e32 v229, 0xffff0000, v230
	v_rcp_f32_e32 v230, v189
	v_add_f32_e32 v189, v163, v193
	v_exp_f32_e32 v193, v191
	v_add_f32_e32 v227, v151, v238
	v_med3_f32 v189, v189, s85, v226
	v_med3_f32 v227, v227, s85, v226
	v_mul_f32_e32 v189, 0xbfb8aa3b, v189
	v_mul_f32_e32 v227, 0xbfb8aa3b, v227
	v_exp_f32_e32 v191, v189
	v_add_f32_e32 v189, 1.0, v193
	v_exp_f32_e32 v227, v227
	v_rcp_f32_e32 v193, v189
	v_add_f32_e32 v189, v155, v229
	v_med3_f32 v189, v189, s85, v226
	v_mul_f32_e32 v189, 0xbfb8aa3b, v189
	v_exp_f32_e32 v229, v189
	v_add_f32_e32 v189, 1.0, v227
	v_add_f32_e32 v227, v160, v236
	v_med3_f32 v227, v227, s85, v226
	v_mul_f32_e32 v227, 0xbfb8aa3b, v227
	v_exp_f32_e32 v227, v227
	v_lshlrev_b32_e32 v243, 16, v231
	v_and_b32_e32 v244, 0xffff0000, v231
	v_rcp_f32_e32 v231, v189
	v_add_f32_e32 v189, v164, v240
	v_med3_f32 v189, v189, s85, v226
	v_mul_f32_e32 v189, 0xbfb8aa3b, v189
	v_exp_f32_e32 v236, v189
	v_add_f32_e32 v189, 1.0, v227
	v_add_f32_e32 v227, v152, v239
	v_med3_f32 v227, v227, s85, v226
	v_mul_f32_e32 v227, 0xbfb8aa3b, v227
	v_exp_f32_e32 v227, v227
	v_add_f32_e32 v237, v161, v237
	v_rcp_f32_e32 v238, v189
	v_add_f32_e32 v189, v156, v243
	v_med3_f32 v237, v237, s85, v226
	v_med3_f32 v189, v189, s85, v226
	v_mul_f32_e32 v237, 0xbfb8aa3b, v237
	v_mul_f32_e32 v189, 0xbfb8aa3b, v189
	v_exp_f32_e32 v239, v237
	v_add_f32_e32 v190, v162, v190
	v_exp_f32_e32 v240, v189
	v_add_f32_e32 v189, 1.0, v227
	v_add_f32_e32 v227, v165, v242
	v_med3_f32 v190, v190, s85, v226
	v_med3_f32 v227, v227, s85, v226
	v_mul_f32_e32 v190, 0xbfb8aa3b, v190
	v_mul_f32_e32 v227, 0xbfb8aa3b, v227
	v_exp_f32_e32 v190, v190
	v_exp_f32_e32 v237, v227
	v_rcp_f32_e32 v242, v189
	v_add_f32_e32 v189, 1.0, v239
	v_rcp_f32_e32 v239, v189
	v_pk_add_f32 v[236:237], v[236:237], 1.0 op_sel_hi:[1,0]
	v_pk_add_f32 v[190:191], v[190:191], 1.0 op_sel_hi:[1,0]
	v_add_f32_e32 v189, v157, v244
	v_pk_mul_f32 v[190:191], v[192:193], v[190:191]
	v_pk_mul_f32 v[192:193], v[238:239], v[236:237]
	v_med3_f32 v189, v189, s85, v226
	v_pk_mul_f32 v[68:69], v[68:69], v[192:193]
	v_add_f32_e32 v192, v153, v241
	v_med3_f32 v192, v192, s85, v226
	v_mul_f32_e32 v192, 0xbfb8aa3b, v192
	v_exp_f32_e32 v192, v192
	v_mul_f32_e32 v189, 0xbfb8aa3b, v189
	v_exp_f32_e32 v241, v189
	v_pk_mul_f32 v[66:67], v[66:67], v[190:191]
	v_add_f32_e32 v189, 1.0, v192
	v_rcp_f32_e32 v243, v189
	v_lshlrev_b32_e32 v189, 16, v194
	v_add_f32_e32 v189, v142, v189
	v_pk_add_f32 v[192:193], v[228:229], 1.0 op_sel_hi:[1,0]
	v_med3_f32 v189, v189, s85, v226
	v_pk_mul_f32 v[192:193], v[230:231], v[192:193]
	v_mul_f32_e32 v189, 0xbfb8aa3b, v189
	v_pk_mul_f32 v[62:63], v[62:63], v[192:193]
	v_lshlrev_b32_e32 v193, 16, v196
	v_exp_f32_e32 v189, v189
	v_add_f32_e32 v193, v134, v193
	v_pk_add_f32 v[190:191], v[240:241], 1.0 op_sel_hi:[1,0]
	v_med3_f32 v193, v193, s85, v226
	v_pk_mul_f32 v[190:191], v[242:243], v[190:191]
	v_mul_f32_e32 v193, 0xbfb8aa3b, v193
	v_pk_mul_f32 v[64:65], v[64:65], v[190:191]
	v_and_b32_e32 v191, 0xffff0000, v194
	s_waitcnt lgkmcnt(0)
	v_lshlrev_b32_e32 v194, 16, v234
	v_add_f32_e32 v189, 1.0, v189
	v_exp_f32_e32 v193, v193
	v_rcp_f32_e32 v192, v189
	v_add_f32_e32 v189, v138, v194
	v_add_f32_e32 v191, v143, v191
	v_med3_f32 v189, v189, s85, v226
	v_med3_f32 v191, v191, s85, v226
	v_mul_f32_e32 v189, 0xbfb8aa3b, v189
	v_mul_f32_e32 v191, 0xbfb8aa3b, v191
	v_lshlrev_b32_e32 v227, 16, v195
	v_and_b32_e32 v229, 0xffff0000, v195
	v_and_b32_e32 v195, 0xffff0000, v196
	v_lshlrev_b32_e32 v231, 16, v197
	v_and_b32_e32 v236, 0xffff0000, v197
	v_and_b32_e32 v197, 0xffff0000, v232
	v_exp_f32_e32 v194, v189
	v_add_f32_e32 v189, 1.0, v193
	v_exp_f32_e32 v193, v191
	v_rcp_f32_e32 v196, v189
	v_add_f32_e32 v189, v147, v197
	v_add_f32_e32 v195, v135, v195
	v_med3_f32 v189, v189, s85, v226
	v_med3_f32 v195, v195, s85, v226
	v_mul_f32_e32 v189, 0xbfb8aa3b, v189
	v_mul_f32_e32 v195, 0xbfb8aa3b, v195
	v_and_b32_e32 v230, 0xffff0000, v234
	v_exp_f32_e32 v191, v189
	v_add_f32_e32 v189, 1.0, v193
	v_exp_f32_e32 v197, v195
	v_rcp_f32_e32 v193, v189
	v_add_f32_e32 v189, v139, v230
	v_add_f32_e32 v227, v144, v227
	v_med3_f32 v189, v189, s85, v226
	v_med3_f32 v227, v227, s85, v226
	v_mul_f32_e32 v189, 0xbfb8aa3b, v189
	v_mul_f32_e32 v227, 0xbfb8aa3b, v227
	v_lshlrev_b32_e32 v228, 16, v233
	v_exp_f32_e32 v195, v189
	v_add_f32_e32 v189, 1.0, v197
	v_exp_f32_e32 v227, v227
	v_rcp_f32_e32 v197, v189
	v_add_f32_e32 v189, v148, v228
	v_med3_f32 v189, v189, s85, v226
	v_mul_f32_e32 v189, 0xbfb8aa3b, v189
	v_exp_f32_e32 v228, v189
	v_add_f32_e32 v189, 1.0, v227
	v_add_f32_e32 v227, v136, v231
	v_med3_f32 v227, v227, s85, v226
	v_mul_f32_e32 v227, 0xbfb8aa3b, v227
	v_lshlrev_b32_e32 v190, 16, v232
	v_lshlrev_b32_e32 v232, 16, v235
	v_exp_f32_e32 v227, v227
	v_add_f32_e32 v229, v145, v229
	v_rcp_f32_e32 v230, v189
	v_add_f32_e32 v189, v140, v232
	v_med3_f32 v229, v229, s85, v226
	v_med3_f32 v189, v189, s85, v226
	v_mul_f32_e32 v229, 0xbfb8aa3b, v229
	v_and_b32_e32 v233, 0xffff0000, v233
	v_mul_f32_e32 v189, 0xbfb8aa3b, v189
	v_exp_f32_e32 v231, v229
	v_add_f32_e32 v190, v146, v190
	v_exp_f32_e32 v232, v189
	v_add_f32_e32 v189, 1.0, v227
	v_add_f32_e32 v227, v149, v233
	v_med3_f32 v190, v190, s85, v226
	v_med3_f32 v227, v227, s85, v226
	v_mul_f32_e32 v190, 0xbfb8aa3b, v190
	v_mul_f32_e32 v227, 0xbfb8aa3b, v227
	v_exp_f32_e32 v190, v190
	v_exp_f32_e32 v229, v227
	v_rcp_f32_e32 v234, v189
	v_add_f32_e32 v189, 1.0, v231
	v_rcp_f32_e32 v231, v189
	v_pk_add_f32 v[228:229], v[228:229], 1.0 op_sel_hi:[1,0]
	v_pk_add_f32 v[190:191], v[190:191], 1.0 op_sel_hi:[1,0]
	v_and_b32_e32 v235, 0xffff0000, v235
	v_pk_mul_f32 v[190:191], v[192:193], v[190:191]
	v_pk_mul_f32 v[192:193], v[230:231], v[228:229]
	v_add_f32_e32 v189, v141, v235
	v_pk_mul_f32 v[60:61], v[60:61], v[192:193]
	v_add_f32_e32 v192, v137, v236
	v_med3_f32 v192, v192, s85, v226
	v_mul_f32_e32 v192, 0xbfb8aa3b, v192
	v_exp_f32_e32 v192, v192
	v_med3_f32 v189, v189, s85, v226
	v_mul_f32_e32 v189, 0xbfb8aa3b, v189
	v_exp_f32_e32 v233, v189
	v_add_f32_e32 v189, 1.0, v192
	v_rcp_f32_e32 v235, v189
	s_waitcnt vmcnt(4)
; #define UNPK0(q_) ((f32x4){bf_lo((q_).x), bf_hi((q_).x), bf_lo((q_).y), bf_hi((q_).y)})
; #define UNPK1(q_) ((f32x4){bf_lo((q_).z), bf_hi((q_).z), bf_lo((q_).w), bf_hi((q_).w)})
;     static __device__ __forceinline__ float eneg(float g) { return __builtin_amdgcn_exp2f(-1.4426950408889634f * fminf(fmaxf(g, -30.f), 30.f)); }
;     __device__ __forceinline__ void mid(f32x4 (&acc)[2][2][4][2], const Unit& u, int wr, int wc, int fr, int fq) const {
;     ...
;             for (int m = 2 * (am & 1); m < 2 * (am & 1) + 2; ++m) { pa.fetch(ai, m, ra[m][0], ra[m][1]); pb.fetch(ai, m, rb[m][0], rb[m][1]); }
;             asm volatile("" ::: "memory");
; #pragma unroll
;             for (int m = 2 * (am & 1); m < 2 * (am & 1) + 2; ++m) {
;                 pa.stage(ra[m][0], ra[m][1]); const u32x4 ga0 = pa.get(0), ga1 = pa.get(1);
;                 asm volatile("" ::: "memory");
;                 pb.stage(rb[m][0], rb[m][1]); const u32x4 gb0 = pb.get(0), gb1 = pb.get(1);
;                 asm volatile("" ::: "memory");
; #pragma unroll
;                 for (int bj = 0; bj < 2; ++bj) { const u32x4 ga = bj ? ga1 : ga0, gb = bj ? gb1 : gb0;
;                     const f32x4 a0 = UNPK0(ga) + ba[bj][0], a1 = UNPK1(ga) + ba[bj][1], b0 = UNPK0(gb) + bb[bj][0], b1 = UNPK1(gb) + bb[bj][1];
; #pragma unroll
;                     for (int k = 0; k < 4; ++k) { acc[ai][bj][m][0][k] *= (1.0f + eneg(b0[k])) * __builtin_amdgcn_rcpf(1.0f + eneg(a0[k]));
;                                                   acc[ai][bj][m][1][k] *= (1.0f + eneg(b1[k])) * __builtin_amdgcn_rcpf(1.0f + eneg(a1[k])); } } }
	ds_write_b128 v3, v[174:177]
	s_waitcnt vmcnt(3)
	ds_write_b128 v3, v[178:181] offset:1152
	ds_read_b128 v[174:177], v188
	ds_read_b128 v[178:181], v188 offset:64
	s_waitcnt vmcnt(2)
	ds_write_b128 v3, v[166:169]
	s_waitcnt vmcnt(1)
	ds_write_b128 v3, v[170:173] offset:1152
	ds_read_b128 v[166:169], v188
	ds_read_b128 v[170:173], v188 offset:64
	v_pk_mul_f32 v[58:59], v[58:59], v[190:191]
	v_pk_add_f32 v[190:191], v[232:233], 1.0 op_sel_hi:[1,0]
	s_waitcnt lgkmcnt(5)
	v_lshlrev_b32_e32 v189, 16, v174
	v_pk_mul_f32 v[190:191], v[234:235], v[190:191]
	s_waitcnt lgkmcnt(1)
	v_lshlrev_b32_e32 v227, 16, v169
	v_pk_mul_f32 v[56:57], v[56:57], v[190:191]
	v_and_b32_e32 v190, 0xffff0000, v174
	v_lshlrev_b32_e32 v174, 16, v176
	v_and_b32_e32 v228, 0xffff0000, v169
	v_add_f32_e32 v169, v150, v174
	v_pk_add_f32 v[192:193], v[194:195], 1.0 op_sel_hi:[1,0]
	v_med3_f32 v169, v169, s85, v226
	v_pk_mul_f32 v[192:193], v[196:197], v[192:193]
	v_mul_f32_e32 v169, 0xbfb8aa3b, v169
	v_pk_mul_f32 v[54:55], v[54:55], v[192:193]
	v_lshlrev_b32_e32 v191, 16, v175
	v_and_b32_e32 v193, 0xffff0000, v175
	v_and_b32_e32 v175, 0xffff0000, v176
	v_lshlrev_b32_e32 v192, 16, v167
	v_and_b32_e32 v196, 0xffff0000, v167
	v_lshlrev_b32_e32 v167, 16, v168
	v_exp_f32_e32 v169, v169
	v_add_f32_e32 v167, v154, v167
	v_add_f32_e32 v175, v151, v175
	v_med3_f32 v167, v167, s85, v226
	v_med3_f32 v175, v175, s85, v226
	v_mul_f32_e32 v167, 0xbfb8aa3b, v167
	v_mul_f32_e32 v175, 0xbfb8aa3b, v175
	v_and_b32_e32 v197, 0xffff0000, v168
	v_add_f32_e32 v168, v158, v189
	v_exp_f32_e32 v174, v167
	v_add_f32_e32 v167, 1.0, v169
	v_add_f32_e32 v169, v159, v190
	v_exp_f32_e32 v189, v175
	v_add_f32_e32 v190, v160, v191
	v_med3_f32 v190, v190, s85, v226
	v_lshlrev_b32_e32 v194, 16, v177
	v_and_b32_e32 v195, 0xffff0000, v177
	v_lshlrev_b32_e32 v176, 16, v166
	v_and_b32_e32 v177, 0xffff0000, v166
	v_mul_f32_e32 v190, 0xbfb8aa3b, v190
	v_add_f32_e32 v166, v162, v176
	v_rcp_f32_e32 v176, v167
	v_add_f32_e32 v167, v163, v177
	v_add_f32_e32 v177, v155, v197
	v_exp_f32_e32 v191, v190
	v_med3_f32 v175, v177, s85, v226
	v_add_f32_e32 v177, 1.0, v189
	v_add_f32_e32 v189, v164, v192
	v_med3_f32 v189, v189, s85, v226
	v_mul_f32_e32 v189, 0xbfb8aa3b, v189
	v_exp_f32_e32 v190, v189
	v_add_f32_e32 v189, 1.0, v191
	v_add_f32_e32 v191, v152, v194
	v_med3_f32 v191, v191, s85, v226
	v_mul_f32_e32 v191, 0xbfb8aa3b, v191
	v_exp_f32_e32 v191, v191
	v_add_f32_e32 v193, v161, v193
	v_med3_f32 v168, v168, s85, v226
	v_med3_f32 v169, v169, s85, v226
	v_rcp_f32_e32 v192, v189
	v_add_f32_e32 v189, v156, v227
	v_med3_f32 v193, v193, s85, v226
	v_mul_f32_e32 v168, 0xbfb8aa3b, v168
	v_mul_f32_e32 v169, 0xbfb8aa3b, v169
	v_med3_f32 v189, v189, s85, v226
	v_mul_f32_e32 v193, 0xbfb8aa3b, v193
	v_exp_f32_e32 v168, v168
	v_exp_f32_e32 v169, v169
	v_mul_f32_e32 v189, 0xbfb8aa3b, v189
	v_exp_f32_e32 v193, v193
	v_exp_f32_e32 v194, v189
	v_add_f32_e32 v189, 1.0, v191
	v_add_f32_e32 v191, v165, v196
	v_med3_f32 v166, v166, s85, v226
	v_med3_f32 v167, v167, s85, v226
	v_med3_f32 v191, v191, s85, v226
	v_mul_f32_e32 v166, 0xbfb8aa3b, v166
	v_mul_f32_e32 v167, 0xbfb8aa3b, v167
	v_mul_f32_e32 v191, 0xbfb8aa3b, v191
	v_exp_f32_e32 v166, v166
	v_add_f32_e32 v168, 1.0, v168
	v_exp_f32_e32 v167, v167
	v_add_f32_e32 v169, 1.0, v169
	v_exp_f32_e32 v191, v191
	v_rcp_f32_e32 v196, v189
	v_add_f32_e32 v189, 1.0, v193
	v_rcp_f32_e32 v168, v168
	v_rcp_f32_e32 v169, v169
	v_rcp_f32_e32 v193, v189
	v_pk_add_f32 v[190:191], v[190:191], 1.0 op_sel_hi:[1,0]
	v_pk_add_f32 v[166:167], v[166:167], 1.0 op_sel_hi:[1,0]
	v_mul_f32_e32 v175, 0xbfb8aa3b, v175
	v_pk_mul_f32 v[166:167], v[168:169], v[166:167]
	v_pk_mul_f32 v[168:169], v[192:193], v[190:191]
	v_pk_mul_f32 v[50:51], v[50:51], v[166:167]
	v_pk_mul_f32 v[52:53], v[52:53], v[168:169]
	v_add_f32_e32 v169, v153, v195
	v_med3_f32 v169, v169, s85, v226
	v_mul_f32_e32 v169, 0xbfb8aa3b, v169
	v_exp_f32_e32 v169, v169
	v_add_f32_e32 v168, v157, v228
	v_med3_f32 v168, v168, s85, v226
	v_mul_f32_e32 v168, 0xbfb8aa3b, v168
	v_exp_f32_e32 v195, v168
	v_add_f32_e32 v166, 1.0, v169
	v_rcp_f32_e32 v197, v166
	v_exp_f32_e32 v175, v175
	v_pk_add_f32 v[166:167], v[194:195], 1.0 op_sel_hi:[1,0]
	v_rcp_f32_e32 v177, v177
	v_pk_mul_f32 v[166:167], v[196:197], v[166:167]
	global_load_dwordx4 v[190:193], v[186:187], off
	global_load_dwordx4 v[194:197], v[186:187], off offset:1024
	global_load_dwordx4 v[228:231], v[4:5], off
	global_load_dwordx4 v[232:235], v[4:5], off offset:1024
	v_pk_add_f32 v[168:169], v[174:175], 1.0 op_sel_hi:[1,0]
	v_pk_mul_f32 v[48:49], v[48:49], v[166:167]
	v_pk_mul_f32 v[168:169], v[176:177], v[168:169]
	v_lshlrev_b32_e32 v166, 16, v178
	v_pk_mul_f32 v[46:47], v[46:47], v[168:169]
	v_lshlrev_b32_e32 v169, 16, v180
	v_add_f32_e32 v169, v134, v169
	v_and_b32_e32 v167, 0xffff0000, v178
	v_add_f32_e32 v166, v142, v166
	v_med3_f32 v169, v169, s85, v226
	v_med3_f32 v166, v166, s85, v226
	v_mul_f32_e32 v169, 0xbfb8aa3b, v169
	v_add_f32_e32 v167, v143, v167
	v_mul_f32_e32 v166, 0xbfb8aa3b, v166
	v_exp_f32_e32 v169, v169
	v_med3_f32 v167, v167, s85, v226
	v_lshlrev_b32_e32 v174, 16, v179
	v_and_b32_e32 v175, 0xffff0000, v179
	v_and_b32_e32 v176, 0xffff0000, v180
	v_lshlrev_b32_e32 v177, 16, v181
	v_and_b32_e32 v179, 0xffff0000, v181
	s_waitcnt lgkmcnt(0)
; #define UNPK0(q_) ((f32x4){bf_lo((q_).x), bf_hi((q_).x), bf_lo((q_).y), bf_hi((q_).y)})
; #define UNPK1(q_) ((f32x4){bf_lo((q_).z), bf_hi((q_).z), bf_lo((q_).w), bf_hi((q_).w)})
;     static __device__ __forceinline__ float eneg(float g) { return __builtin_amdgcn_exp2f(-1.4426950408889634f * fminf(fmaxf(g, -30.f), 30.f)); }
;     __device__ __forceinline__ void mid(f32x4 (&acc)[2][2][4][2], const Unit& u, int wr, int wc, int fr, int fq) const {
;     ...
;             for (int m = 2 * (am & 1); m < 2 * (am & 1) + 2; ++m) {
;                 pa.stage(ra[m][0], ra[m][1]); const u32x4 ga0 = pa.get(0), ga1 = pa.get(1);
;                 asm volatile("" ::: "memory");
;                 pb.stage(rb[m][0], rb[m][1]); const u32x4 gb0 = pb.get(0), gb1 = pb.get(1);
;                 asm volatile("" ::: "memory");
; #pragma unroll
;                 for (int bj = 0; bj < 2; ++bj) { const u32x4 ga = bj ? ga1 : ga0, gb = bj ? gb1 : gb0;
;                     const f32x4 a0 = UNPK0(ga) + ba[bj][0], a1 = UNPK1(ga) + ba[bj][1], b0 = UNPK0(gb) + bb[bj][0], b1 = UNPK1(gb) + bb[bj][1];
; #pragma unroll
;                     for (int k = 0; k < 4; ++k) { acc[ai][bj][m][0][k] *= (1.0f + eneg(b0[k])) * __builtin_amdgcn_rcpf(1.0f + eneg(a0[k]));
;                                                   acc[ai][bj][m][1][k] *= (1.0f + eneg(b1[k])) * __builtin_amdgcn_rcpf(1.0f + eneg(a1[k])); } } }
	v_lshlrev_b32_e32 v168, 16, v170
	v_and_b32_e32 v178, 0xffff0000, v170
	v_lshlrev_b32_e32 v180, 16, v171
	v_and_b32_e32 v181, 0xffff0000, v171
	v_lshlrev_b32_e32 v170, 16, v172
	v_and_b32_e32 v171, 0xffff0000, v172
	v_exp_f32_e32 v172, v166
	v_mul_f32_e32 v167, 0xbfb8aa3b, v167
	v_lshlrev_b32_e32 v189, 16, v173
	v_and_b32_e32 v227, 0xffff0000, v173
	v_exp_f32_e32 v173, v167
	v_add_f32_e32 v177, v136, v177
	v_add_f32_e32 v174, v144, v174
	v_med3_f32 v177, v177, s85, v226
	v_add_f32_e32 v175, v145, v175
	v_add_f32_e32 v168, v146, v168
	v_add_f32_e32 v169, 1.0, v169
	v_med3_f32 v174, v174, s85, v226
	v_mul_f32_e32 v177, 0xbfb8aa3b, v177
	v_med3_f32 v175, v175, s85, v226
	v_med3_f32 v166, v168, s85, v226
	v_add_f32_e32 v168, 1.0, v172
	v_rcp_f32_e32 v172, v169
	v_add_f32_e32 v169, v147, v178
	v_mul_f32_e32 v174, 0xbfb8aa3b, v174
	v_exp_f32_e32 v177, v177
	v_mul_f32_e32 v175, 0xbfb8aa3b, v175
	v_med3_f32 v167, v169, s85, v226
	v_add_f32_e32 v169, 1.0, v173
	v_add_f32_e32 v173, v135, v176
	v_add_f32_e32 v176, v148, v180
	v_exp_f32_e32 v178, v174
	v_add_f32_e32 v180, v149, v181
	v_exp_f32_e32 v181, v175
	v_med3_f32 v174, v176, s85, v226
	v_med3_f32 v180, v180, s85, v226
	v_mul_f32_e32 v166, 0xbfb8aa3b, v166
	v_mul_f32_e32 v167, 0xbfb8aa3b, v167
	v_mul_f32_e32 v174, 0xbfb8aa3b, v174
	v_add_f32_e32 v177, 1.0, v177
	v_mul_f32_e32 v175, 0xbfb8aa3b, v180
	v_exp_f32_e32 v166, v166
	v_exp_f32_e32 v167, v167
	v_exp_f32_e32 v174, v174
	v_add_f32_e32 v176, 1.0, v178
	v_exp_f32_e32 v175, v175
	v_rcp_f32_e32 v180, v177
	v_add_f32_e32 v177, 1.0, v181
	v_rcp_f32_e32 v168, v168
	v_rcp_f32_e32 v169, v169
	v_rcp_f32_e32 v176, v176
	v_rcp_f32_e32 v177, v177
	v_pk_add_f32 v[174:175], v[174:175], 1.0 op_sel_hi:[1,0]
	v_pk_add_f32 v[166:167], v[166:167], 1.0 op_sel_hi:[1,0]
	v_med3_f32 v173, v173, s85, v226
	v_pk_mul_f32 v[166:167], v[168:169], v[166:167]
	v_pk_mul_f32 v[168:169], v[176:177], v[174:175]
	v_mul_f32_e32 v173, 0xbfb8aa3b, v173
	v_pk_mul_f32 v[44:45], v[44:45], v[168:169]
	v_add_f32_e32 v169, v137, v179
	v_med3_f32 v169, v169, s85, v226
	v_mul_f32_e32 v169, 0xbfb8aa3b, v169
	v_exp_f32_e32 v173, v173
	v_exp_f32_e32 v169, v169
	v_add_f32_e32 v170, v138, v170
	v_add_f32_e32 v171, v139, v171
	v_add_f32_e32 v178, v140, v189
	v_add_f32_e32 v168, v141, v227
	v_med3_f32 v170, v170, s85, v226
	v_med3_f32 v171, v171, s85, v226
	v_med3_f32 v178, v178, s85, v226
	v_med3_f32 v168, v168, s85, v226
	v_mul_f32_e32 v170, 0xbfb8aa3b, v170
	v_mul_f32_e32 v171, 0xbfb8aa3b, v171
	v_mul_f32_e32 v178, 0xbfb8aa3b, v178
	v_mul_f32_e32 v168, 0xbfb8aa3b, v168
	v_exp_f32_e32 v170, v170
	v_exp_f32_e32 v171, v171
	v_add_f32_e32 v173, 1.0, v173
	v_exp_f32_e32 v178, v178
	v_exp_f32_e32 v179, v168
	v_pk_mul_f32 v[42:43], v[42:43], v[166:167]
	v_add_f32_e32 v166, 1.0, v169
	v_rcp_f32_e32 v173, v173
	v_rcp_f32_e32 v181, v166
	v_pk_add_f32 v[166:167], v[178:179], 1.0 op_sel_hi:[1,0]
	v_pk_add_f32 v[168:169], v[170:171], 1.0 op_sel_hi:[1,0]
	v_pk_mul_f32 v[166:167], v[180:181], v[166:167]
	v_pk_mul_f32 v[168:169], v[172:173], v[168:169]
	v_pk_mul_f32 v[40:41], v[40:41], v[166:167]
	v_pk_mul_f32 v[38:39], v[38:39], v[168:169]
	global_load_dwordx4 v[174:177], v[186:187], off offset:2048
	global_load_dwordx4 v[178:181], v[186:187], off offset:3072
	global_load_dwordx4 v[166:169], v[4:5], off offset:2048
	global_load_dwordx4 v[170:173], v[4:5], off offset:3072
	s_waitcnt vmcnt(7)
	ds_write_b128 v3, v[190:193]
	s_waitcnt vmcnt(6)
	ds_write_b128 v3, v[194:197] offset:1152
	ds_read_b128 v[190:193], v188
	ds_read_b128 v[194:197], v188 offset:64
	s_waitcnt vmcnt(5)
	ds_write_b128 v3, v[228:231]
	s_waitcnt vmcnt(4)
	ds_write_b128 v3, v[232:235] offset:1152
	ds_read_b128 v[228:231], v188
	ds_read_b128 v[232:235], v188 offset:64
	s_waitcnt lgkmcnt(5)
	v_lshlrev_b32_e32 v187, 16, v192
	v_lshlrev_b32_e32 v4, 16, v190
	v_add_f32_e32 v187, v150, v187
	v_add_f32_e32 v4, v158, v4
	v_med3_f32 v187, v187, s85, v226
	v_med3_f32 v4, v4, s85, v226
	v_mul_f32_e32 v187, 0xbfb8aa3b, v187
	v_mul_f32_e32 v4, 0xbfb8aa3b, v4
	v_exp_f32_e32 v187, v187
	v_and_b32_e32 v5, 0xffff0000, v190
	v_lshlrev_b32_e32 v189, 16, v191
	v_and_b32_e32 v227, 0xffff0000, v191
	v_and_b32_e32 v191, 0xffff0000, v192
	v_exp_f32_e32 v192, v4
	v_add_f32_e32 v5, v159, v5
	s_waitcnt lgkmcnt(1)
; #define UNPK0(q_) ((f32x4){bf_lo((q_).x), bf_hi((q_).x), bf_lo((q_).y), bf_hi((q_).y)})
; #define UNPK1(q_) ((f32x4){bf_lo((q_).z), bf_hi((q_).z), bf_lo((q_).w), bf_hi((q_).w)})
;     static __device__ __forceinline__ float eneg(float g) { return __builtin_amdgcn_exp2f(-1.4426950408889634f * fminf(fmaxf(g, -30.f), 30.f)); }
;     __device__ __forceinline__ void mid(f32x4 (&acc)[2][2][4][2], const Unit& u, int wr, int wc, int fr, int fq) const {
;     ...
;                 for (int bj = 0; bj < 2; ++bj) { const u32x4 ga = bj ? ga1 : ga0, gb = bj ? gb1 : gb0;
;                     const f32x4 a0 = UNPK0(ga) + ba[bj][0], a1 = UNPK1(ga) + ba[bj][1], b0 = UNPK0(gb) + bb[bj][0], b1 = UNPK1(gb) + bb[bj][1];
; #pragma unroll
;                     for (int k = 0; k < 4; ++k) { acc[ai][bj][m][0][k] *= (1.0f + eneg(b0[k])) * __builtin_amdgcn_rcpf(1.0f + eneg(a0[k]));
;                                                   acc[ai][bj][m][1][k] *= (1.0f + eneg(b1[k])) * __builtin_amdgcn_rcpf(1.0f + eneg(a1[k])); } } }
	v_lshlrev_b32_e32 v186, 16, v228
	v_med3_f32 v5, v5, s85, v226
	v_lshlrev_b32_e32 v236, 16, v193
	v_and_b32_e32 v237, 0xffff0000, v193
	v_and_b32_e32 v193, 0xffff0000, v228
	v_add_f32_e32 v186, v162, v186
	v_add_f32_e32 v187, 1.0, v187
	v_mul_f32_e32 v5, 0xbfb8aa3b, v5
	v_med3_f32 v4, v186, s85, v226
	v_add_f32_e32 v186, 1.0, v192
	v_rcp_f32_e32 v192, v187
	v_add_f32_e32 v187, v163, v193
	v_exp_f32_e32 v193, v5
	v_add_f32_e32 v189, v160, v189
	v_add_f32_e32 v191, v151, v191
	v_med3_f32 v189, v189, s85, v226
	v_med3_f32 v191, v191, s85, v226
	v_mul_f32_e32 v189, 0xbfb8aa3b, v189
	v_lshlrev_b32_e32 v190, 16, v230
	v_and_b32_e32 v230, 0xffff0000, v230
	v_mul_f32_e32 v191, 0xbfb8aa3b, v191
	v_exp_f32_e32 v189, v189
	v_lshlrev_b32_e32 v238, 16, v231
	v_and_b32_e32 v239, 0xffff0000, v231
	v_med3_f32 v5, v187, s85, v226
	v_add_f32_e32 v187, 1.0, v193
	v_add_f32_e32 v193, v155, v230
	v_exp_f32_e32 v230, v191
	v_add_f32_e32 v231, v152, v236
	v_med3_f32 v231, v231, s85, v226
	v_add_f32_e32 v227, v161, v227
	v_mul_f32_e32 v231, 0xbfb8aa3b, v231
	v_med3_f32 v227, v227, s85, v226
	v_add_f32_e32 v189, 1.0, v189
	v_exp_f32_e32 v231, v231
	v_mul_f32_e32 v227, 0xbfb8aa3b, v227
	v_lshlrev_b32_e32 v228, 16, v229
	v_and_b32_e32 v229, 0xffff0000, v229
	v_med3_f32 v191, v193, s85, v226
	v_add_f32_e32 v193, 1.0, v230
	v_rcp_f32_e32 v230, v189
	v_add_f32_e32 v189, v156, v238
	v_exp_f32_e32 v227, v227
	v_add_f32_e32 v228, v164, v228
	v_med3_f32 v189, v189, s85, v226
	v_add_f32_e32 v229, v165, v229
	v_med3_f32 v228, v228, s85, v226
	v_mul_f32_e32 v189, 0xbfb8aa3b, v189
	v_med3_f32 v229, v229, s85, v226
	v_mul_f32_e32 v4, 0xbfb8aa3b, v4
	v_mul_f32_e32 v5, 0xbfb8aa3b, v5
	v_mul_f32_e32 v228, 0xbfb8aa3b, v228
	v_exp_f32_e32 v236, v189
	v_add_f32_e32 v189, 1.0, v231
	v_mul_f32_e32 v229, 0xbfb8aa3b, v229
	v_exp_f32_e32 v4, v4
	v_exp_f32_e32 v5, v5
	v_exp_f32_e32 v228, v228
	v_exp_f32_e32 v229, v229
	v_rcp_f32_e32 v238, v189
	v_add_f32_e32 v189, 1.0, v227
	v_rcp_f32_e32 v186, v186
	v_rcp_f32_e32 v187, v187
	v_rcp_f32_e32 v231, v189
	v_pk_add_f32 v[228:229], v[228:229], 1.0 op_sel_hi:[1,0]
	v_pk_add_f32 v[4:5], v[4:5], 1.0 op_sel_hi:[1,0]
	v_add_f32_e32 v190, v154, v190
	v_pk_mul_f32 v[4:5], v[186:187], v[4:5]
	v_pk_mul_f32 v[186:187], v[230:231], v[228:229]
	v_med3_f32 v190, v190, s85, v226
	v_pk_mul_f32 v[36:37], v[36:37], v[186:187]
	v_add_f32_e32 v187, v153, v237
	v_med3_f32 v187, v187, s85, v226
	v_mul_f32_e32 v187, 0xbfb8aa3b, v187
	v_exp_f32_e32 v187, v187
	v_add_f32_e32 v186, v157, v239
	v_mul_f32_e32 v190, 0xbfb8aa3b, v190
	v_mul_f32_e32 v191, 0xbfb8aa3b, v191
	v_med3_f32 v186, v186, s85, v226
	v_exp_f32_e32 v190, v190
	v_exp_f32_e32 v191, v191
	v_mul_f32_e32 v186, 0xbfb8aa3b, v186
	v_rcp_f32_e32 v193, v193
	v_exp_f32_e32 v237, v186
	v_pk_mul_f32 v[34:35], v[34:35], v[4:5]
	v_add_f32_e32 v4, 1.0, v187
	v_rcp_f32_e32 v239, v4
	v_pk_add_f32 v[186:187], v[190:191], 1.0 op_sel_hi:[1,0]
	v_pk_add_f32 v[4:5], v[236:237], 1.0 op_sel_hi:[1,0]
	v_pk_mul_f32 v[186:187], v[192:193], v[186:187]
	v_pk_mul_f32 v[4:5], v[238:239], v[4:5]
	v_pk_mul_f32 v[30:31], v[30:31], v[186:187]
	v_lshlrev_b32_e32 v187, 16, v196
	v_pk_mul_f32 v[32:33], v[32:33], v[4:5]
	v_lshlrev_b32_e32 v4, 16, v194
	v_add_f32_e32 v187, v134, v187
	v_add_f32_e32 v4, v142, v4
	v_med3_f32 v187, v187, s85, v226
	v_med3_f32 v4, v4, s85, v226
	v_mul_f32_e32 v187, 0xbfb8aa3b, v187
	v_mul_f32_e32 v4, 0xbfb8aa3b, v4
	v_exp_f32_e32 v187, v187
	v_and_b32_e32 v5, 0xffff0000, v194
	v_exp_f32_e32 v192, v4
	v_add_f32_e32 v5, v143, v5
	s_waitcnt lgkmcnt(0)
	v_lshlrev_b32_e32 v186, 16, v232
	v_med3_f32 v5, v5, s85, v226
	v_lshlrev_b32_e32 v189, 16, v195
	v_and_b32_e32 v193, 0xffff0000, v232
	v_add_f32_e32 v186, v146, v186
	v_add_f32_e32 v187, 1.0, v187
	v_mul_f32_e32 v5, 0xbfb8aa3b, v5
	v_and_b32_e32 v191, 0xffff0000, v196
	v_med3_f32 v4, v186, s85, v226
	v_add_f32_e32 v186, 1.0, v192
	v_rcp_f32_e32 v192, v187
	v_add_f32_e32 v187, v147, v193
	v_exp_f32_e32 v193, v5
	v_add_f32_e32 v189, v144, v189
	v_add_f32_e32 v191, v135, v191
	v_med3_f32 v189, v189, s85, v226
	v_med3_f32 v191, v191, s85, v226
	v_mul_f32_e32 v189, 0xbfb8aa3b, v189
	v_lshlrev_b32_e32 v227, 16, v197
	v_and_b32_e32 v196, 0xffff0000, v234
	v_mul_f32_e32 v191, 0xbfb8aa3b, v191
	v_exp_f32_e32 v189, v189
	v_med3_f32 v5, v187, s85, v226
	v_add_f32_e32 v187, 1.0, v193
	v_add_f32_e32 v193, v139, v196
	v_exp_f32_e32 v196, v191
	v_add_f32_e32 v227, v136, v227
	v_med3_f32 v227, v227, s85, v226
	v_mul_f32_e32 v227, 0xbfb8aa3b, v227
	v_and_b32_e32 v195, 0xffff0000, v195
	v_lshlrev_b32_e32 v228, 16, v235
	v_add_f32_e32 v189, 1.0, v189
	v_exp_f32_e32 v227, v227
	v_med3_f32 v191, v193, s85, v226
	v_add_f32_e32 v193, 1.0, v196
	v_rcp_f32_e32 v196, v189
	v_add_f32_e32 v189, v140, v228
	v_add_f32_e32 v195, v145, v195
	v_med3_f32 v189, v189, s85, v226
	v_med3_f32 v195, v195, s85, v226
	v_mul_f32_e32 v189, 0xbfb8aa3b, v189
	v_mul_f32_e32 v195, 0xbfb8aa3b, v195
	v_and_b32_e32 v229, 0xffff0000, v197
	v_lshlrev_b32_e32 v194, 16, v233
	v_and_b32_e32 v197, 0xffff0000, v233
	v_exp_f32_e32 v228, v189
	v_add_f32_e32 v189, 1.0, v227
	v_exp_f32_e32 v227, v195
	v_add_f32_e32 v194, v148, v194
	v_add_f32_e32 v197, v149, v197
	v_med3_f32 v194, v194, s85, v226
	v_med3_f32 v197, v197, s85, v226
	v_mul_f32_e32 v4, 0xbfb8aa3b, v4
	v_mul_f32_e32 v5, 0xbfb8aa3b, v5
	v_mul_f32_e32 v194, 0xbfb8aa3b, v194
	v_mul_f32_e32 v195, 0xbfb8aa3b, v197
	v_exp_f32_e32 v4, v4
	v_exp_f32_e32 v5, v5
	v_exp_f32_e32 v194, v194
	v_exp_f32_e32 v195, v195
	v_rcp_f32_e32 v230, v189
	v_add_f32_e32 v189, 1.0, v227
	v_rcp_f32_e32 v186, v186
	v_rcp_f32_e32 v187, v187
	v_rcp_f32_e32 v197, v189
	v_pk_add_f32 v[194:195], v[194:195], 1.0 op_sel_hi:[1,0]
	v_pk_add_f32 v[4:5], v[4:5], 1.0 op_sel_hi:[1,0]
	v_lshlrev_b32_e32 v190, 16, v234
	v_pk_mul_f32 v[4:5], v[186:187], v[4:5]
	v_pk_mul_f32 v[186:187], v[196:197], v[194:195]
	s_waitcnt vmcnt(3)
; #define UNPK0(q_) ((f32x4){bf_lo((q_).x), bf_hi((q_).x), bf_lo((q_).y), bf_hi((q_).y)})
; #define UNPK1(q_) ((f32x4){bf_lo((q_).z), bf_hi((q_).z), bf_lo((q_).w), bf_hi((q_).w)})
;     static __device__ __forceinline__ float eneg(float g) { return __builtin_amdgcn_exp2f(-1.4426950408889634f * fminf(fmaxf(g, -30.f), 30.f)); }
;     __device__ __forceinline__ void mid(f32x4 (&acc)[2][2][4][2], const Unit& u, int wr, int wc, int fr, int fq) const {
;     ...
;             for (int m = 2 * (am & 1); m < 2 * (am & 1) + 2; ++m) {
;                 pa.stage(ra[m][0], ra[m][1]); const u32x4 ga0 = pa.get(0), ga1 = pa.get(1);
;                 asm volatile("" ::: "memory");
;                 pb.stage(rb[m][0], rb[m][1]); const u32x4 gb0 = pb.get(0), gb1 = pb.get(1);
;                 asm volatile("" ::: "memory");
; #pragma unroll
;                 for (int bj = 0; bj < 2; ++bj) { const u32x4 ga = bj ? ga1 : ga0, gb = bj ? gb1 : gb0;
;                     const f32x4 a0 = UNPK0(ga) + ba[bj][0], a1 = UNPK1(ga) + ba[bj][1], b0 = UNPK0(gb) + bb[bj][0], b1 = UNPK1(gb) + bb[bj][1];
; #pragma unroll
;                     for (int k = 0; k < 4; ++k) { acc[ai][bj][m][0][k] *= (1.0f + eneg(b0[k])) * __builtin_amdgcn_rcpf(1.0f + eneg(a0[k]));
;                                                   acc[ai][bj][m][1][k] *= (1.0f + eneg(b1[k])) * __builtin_amdgcn_rcpf(1.0f + eneg(a1[k])); } } }
	ds_write_b128 v3, v[174:177]
	s_waitcnt vmcnt(2)
	ds_write_b128 v3, v[178:181] offset:1152
	v_add_f32_e32 v190, v138, v190
	v_pk_mul_f32 v[28:29], v[28:29], v[186:187]
	v_add_f32_e32 v187, v137, v229
	ds_read_b128 v[174:177], v188
	ds_read_b128 v[178:181], v188 offset:64
	v_med3_f32 v190, v190, s85, v226
	v_med3_f32 v187, v187, s85, v226
	v_mul_f32_e32 v190, 0xbfb8aa3b, v190
	v_mul_f32_e32 v191, 0xbfb8aa3b, v191
	v_mul_f32_e32 v187, 0xbfb8aa3b, v187
	v_and_b32_e32 v231, 0xffff0000, v235
	v_exp_f32_e32 v190, v190
	v_exp_f32_e32 v191, v191
	v_exp_f32_e32 v187, v187
	v_rcp_f32_e32 v193, v193
	v_add_f32_e32 v186, v141, v231
	s_waitcnt vmcnt(1)
	ds_write_b128 v3, v[166:169]
	s_waitcnt vmcnt(0)
	ds_write_b128 v3, v[170:173] offset:1152
	s_waitcnt lgkmcnt(3)
	v_lshlrev_b32_e32 v3, 16, v174
	v_med3_f32 v186, v186, s85, v226
	v_add_f32_e32 v3, v158, v3
	v_mul_f32_e32 v186, 0xbfb8aa3b, v186
	v_med3_f32 v3, v3, s85, v226
	v_exp_f32_e32 v229, v186
	v_pk_mul_f32 v[26:27], v[26:27], v[4:5]
	v_add_f32_e32 v4, 1.0, v187
	v_pk_add_f32 v[186:187], v[190:191], 1.0 op_sel_hi:[1,0]
	v_mul_f32_e32 v3, 0xbfb8aa3b, v3
	v_rcp_f32_e32 v231, v4
	v_pk_mul_f32 v[186:187], v[192:193], v[186:187]
	ds_read_b128 v[166:169], v188
	ds_read_b128 v[170:173], v188 offset:64
	v_exp_f32_e32 v3, v3
	v_pk_mul_f32 v[22:23], v[22:23], v[186:187]
	v_lshlrev_b32_e32 v186, 16, v176
	v_add_f32_e32 v150, v150, v186
	v_pk_add_f32 v[4:5], v[228:229], 1.0 op_sel_hi:[1,0]
	v_med3_f32 v150, v150, s85, v226
	v_pk_mul_f32 v[4:5], v[230:231], v[4:5]
	s_waitcnt lgkmcnt(1)
	v_lshlrev_b32_e32 v189, 16, v168
	v_add_f32_e32 v3, 1.0, v3
	v_mul_f32_e32 v150, 0xbfb8aa3b, v150
	v_pk_mul_f32 v[24:25], v[24:25], v[4:5]
	v_and_b32_e32 v5, 0xffff0000, v174
	v_rcp_f32_e32 v158, v3
	v_add_f32_e32 v3, v154, v189
	v_exp_f32_e32 v154, v150
	v_add_f32_e32 v5, v159, v5
	v_med3_f32 v3, v3, s85, v226
	v_med3_f32 v5, v5, s85, v226
	v_mul_f32_e32 v3, 0xbfb8aa3b, v3
	v_mul_f32_e32 v5, 0xbfb8aa3b, v5
	v_lshlrev_b32_e32 v4, 16, v166
	v_and_b32_e32 v166, 0xffff0000, v166
	v_exp_f32_e32 v150, v3
	v_add_f32_e32 v3, 1.0, v154
	v_exp_f32_e32 v159, v5
	v_and_b32_e32 v176, 0xffff0000, v176
	v_rcp_f32_e32 v154, v3
	v_add_f32_e32 v3, v163, v166
	v_med3_f32 v3, v3, s85, v226
	v_add_f32_e32 v151, v151, v176
	v_mul_f32_e32 v3, 0xbfb8aa3b, v3
	v_med3_f32 v151, v151, s85, v226
	v_and_b32_e32 v168, 0xffff0000, v168
	v_exp_f32_e32 v5, v3
	v_add_f32_e32 v3, 1.0, v159
	v_mul_f32_e32 v151, 0xbfb8aa3b, v151
	v_lshlrev_b32_e32 v174, 16, v175
	v_rcp_f32_e32 v159, v3
	v_add_f32_e32 v3, v155, v168
	v_exp_f32_e32 v155, v151
	v_add_f32_e32 v160, v160, v174
	v_med3_f32 v3, v3, s85, v226
	v_med3_f32 v160, v160, s85, v226
	v_mul_f32_e32 v3, 0xbfb8aa3b, v3
	v_mul_f32_e32 v160, 0xbfb8aa3b, v160
	v_lshlrev_b32_e32 v188, 16, v167
	v_add_f32_e32 v4, v162, v4
	v_exp_f32_e32 v151, v3
	v_add_f32_e32 v3, 1.0, v155
	v_exp_f32_e32 v162, v160
	v_lshlrev_b32_e32 v187, 16, v177
	v_rcp_f32_e32 v155, v3
	v_add_f32_e32 v3, v164, v188
	v_med3_f32 v3, v3, s85, v226
	v_add_f32_e32 v152, v152, v187
	v_mul_f32_e32 v3, 0xbfb8aa3b, v3
	v_med3_f32 v152, v152, s85, v226
	v_and_b32_e32 v175, 0xffff0000, v175
	v_lshlrev_b32_e32 v190, 16, v169
	v_exp_f32_e32 v160, v3
	v_add_f32_e32 v3, 1.0, v162
	v_mul_f32_e32 v152, 0xbfb8aa3b, v152
	v_rcp_f32_e32 v162, v3
	v_add_f32_e32 v3, v156, v190
	v_exp_f32_e32 v156, v152
	v_add_f32_e32 v161, v161, v175
	v_med3_f32 v161, v161, s85, v226
	v_med3_f32 v3, v3, s85, v226
	v_mul_f32_e32 v161, 0xbfb8aa3b, v161
	v_and_b32_e32 v167, 0xffff0000, v167
	v_mul_f32_e32 v3, 0xbfb8aa3b, v3
	v_exp_f32_e32 v163, v161
	v_and_b32_e32 v177, 0xffff0000, v177
	v_exp_f32_e32 v152, v3
	v_add_f32_e32 v3, 1.0, v156
	v_add_f32_e32 v156, v165, v167
	v_med3_f32 v156, v156, s85, v226
	v_add_f32_e32 v153, v153, v177
	v_mul_f32_e32 v156, 0xbfb8aa3b, v156
	v_med3_f32 v153, v153, s85, v226
	v_and_b32_e32 v169, 0xffff0000, v169
	v_exp_f32_e32 v161, v156
	v_rcp_f32_e32 v156, v3
	v_add_f32_e32 v3, 1.0, v163
	v_mul_f32_e32 v153, 0xbfb8aa3b, v153
	v_rcp_f32_e32 v163, v3
	v_add_f32_e32 v3, v157, v169
	v_exp_f32_e32 v157, v153
	v_med3_f32 v4, v4, s85, v226
	v_med3_f32 v3, v3, s85, v226
	v_mul_f32_e32 v4, 0xbfb8aa3b, v4
	v_mul_f32_e32 v3, 0xbfb8aa3b, v3
	v_exp_f32_e32 v4, v4
	v_exp_f32_e32 v153, v3
	v_add_f32_e32 v3, 1.0, v157
	v_rcp_f32_e32 v157, v3
	v_lshlrev_b32_e32 v3, 16, v178
	v_add_f32_e32 v3, v142, v3
	v_med3_f32 v3, v3, s85, v226
	v_pk_add_f32 v[4:5], v[4:5], 1.0 op_sel_hi:[1,0]
	v_mul_f32_e32 v3, 0xbfb8aa3b, v3
	v_pk_mul_f32 v[4:5], v[158:159], v[4:5]
	v_exp_f32_e32 v3, v3
	v_pk_mul_f32 v[18:19], v[18:19], v[4:5]
	v_pk_add_f32 v[4:5], v[152:153], 1.0 op_sel_hi:[1,0]
	v_lshlrev_b32_e32 v152, 16, v180
	v_pk_add_f32 v[160:161], v[160:161], 1.0 op_sel_hi:[1,0]
	v_add_f32_e32 v134, v134, v152
	v_pk_mul_f32 v[158:159], v[162:163], v[160:161]
	v_med3_f32 v134, v134, s85, v226
	v_pk_mul_f32 v[20:21], v[20:21], v[158:159]
	v_pk_mul_f32 v[4:5], v[156:157], v[4:5]
	s_waitcnt lgkmcnt(0)
; #define UNPK0(q_) ((f32x4){bf_lo((q_).x), bf_hi((q_).x), bf_lo((q_).y), bf_hi((q_).y)})
; #define UNPK1(q_) ((f32x4){bf_lo((q_).z), bf_hi((q_).z), bf_lo((q_).w), bf_hi((q_).w)})
;     static __device__ __forceinline__ float eneg(float g) { return __builtin_amdgcn_exp2f(-1.4426950408889634f * fminf(fmaxf(g, -30.f), 30.f)); }
;     __device__ __forceinline__ void mid(f32x4 (&acc)[2][2][4][2], const Unit& u, int wr, int wc, int fr, int fq) const {
;     ...
;                 for (int bj = 0; bj < 2; ++bj) { const u32x4 ga = bj ? ga1 : ga0, gb = bj ? gb1 : gb0;
;                     const f32x4 a0 = UNPK0(ga) + ba[bj][0], a1 = UNPK1(ga) + ba[bj][1], b0 = UNPK0(gb) + bb[bj][0], b1 = UNPK1(gb) + bb[bj][1];
; #pragma unroll
;                     for (int k = 0; k < 4; ++k) { acc[ai][bj][m][0][k] *= (1.0f + eneg(b0[k])) * __builtin_amdgcn_rcpf(1.0f + eneg(a0[k]));
;                                                   acc[ai][bj][m][1][k] *= (1.0f + eneg(b1[k])) * __builtin_amdgcn_rcpf(1.0f + eneg(a1[k])); } } }
	v_lshlrev_b32_e32 v159, 16, v172
	v_add_f32_e32 v3, 1.0, v3
	v_mul_f32_e32 v134, 0xbfb8aa3b, v134
	v_pk_mul_f32 v[16:17], v[16:17], v[4:5]
	v_and_b32_e32 v5, 0xffff0000, v178
	v_rcp_f32_e32 v142, v3
	v_add_f32_e32 v3, v138, v159
	v_exp_f32_e32 v138, v134
	v_add_f32_e32 v5, v143, v5
	v_med3_f32 v3, v3, s85, v226
	v_med3_f32 v5, v5, s85, v226
	v_mul_f32_e32 v3, 0xbfb8aa3b, v3
	v_mul_f32_e32 v5, 0xbfb8aa3b, v5
	v_and_b32_e32 v156, 0xffff0000, v170
	v_exp_f32_e32 v134, v3
	v_add_f32_e32 v3, 1.0, v138
	v_exp_f32_e32 v143, v5
	v_and_b32_e32 v153, 0xffff0000, v180
	v_rcp_f32_e32 v138, v3
	v_add_f32_e32 v3, v147, v156
	v_med3_f32 v3, v3, s85, v226
	v_add_f32_e32 v135, v135, v153
	v_pk_add_f32 v[150:151], v[150:151], 1.0 op_sel_hi:[1,0]
	v_mul_f32_e32 v3, 0xbfb8aa3b, v3
	v_med3_f32 v135, v135, s85, v226
	v_pk_mul_f32 v[150:151], v[154:155], v[150:151]
	v_and_b32_e32 v160, 0xffff0000, v172
	v_exp_f32_e32 v5, v3
	v_add_f32_e32 v3, 1.0, v143
	v_mul_f32_e32 v135, 0xbfb8aa3b, v135
	v_pk_mul_f32 v[14:15], v[14:15], v[150:151]
	v_lshlrev_b32_e32 v150, 16, v179
	v_rcp_f32_e32 v143, v3
	v_add_f32_e32 v3, v139, v160
	v_exp_f32_e32 v139, v135
	v_add_f32_e32 v144, v144, v150
	v_med3_f32 v3, v3, s85, v226
	v_med3_f32 v144, v144, s85, v226
	v_lshlrev_b32_e32 v4, 16, v170
	v_mul_f32_e32 v3, 0xbfb8aa3b, v3
	v_mul_f32_e32 v144, 0xbfb8aa3b, v144
	v_lshlrev_b32_e32 v157, 16, v171
	v_add_f32_e32 v4, v146, v4
	v_exp_f32_e32 v135, v3
	v_add_f32_e32 v3, 1.0, v139
	v_exp_f32_e32 v146, v144
	v_lshlrev_b32_e32 v154, 16, v181
	v_rcp_f32_e32 v139, v3
	v_add_f32_e32 v3, v148, v157
	v_med3_f32 v3, v3, s85, v226
	v_add_f32_e32 v136, v136, v154
	v_mul_f32_e32 v3, 0xbfb8aa3b, v3
	v_med3_f32 v136, v136, s85, v226
	v_and_b32_e32 v151, 0xffff0000, v179
	v_lshlrev_b32_e32 v161, 16, v173
	v_exp_f32_e32 v144, v3
	v_add_f32_e32 v3, 1.0, v146
	v_mul_f32_e32 v136, 0xbfb8aa3b, v136
	v_rcp_f32_e32 v146, v3
	v_add_f32_e32 v3, v140, v161
	v_exp_f32_e32 v140, v136
	v_add_f32_e32 v145, v145, v151
	v_med3_f32 v145, v145, s85, v226
	v_med3_f32 v3, v3, s85, v226
	v_mul_f32_e32 v145, 0xbfb8aa3b, v145
	v_and_b32_e32 v158, 0xffff0000, v171
	v_mul_f32_e32 v3, 0xbfb8aa3b, v3
	v_exp_f32_e32 v147, v145
	v_and_b32_e32 v155, 0xffff0000, v181
	v_exp_f32_e32 v136, v3
	v_add_f32_e32 v3, 1.0, v140
	v_add_f32_e32 v140, v149, v158
	v_med3_f32 v140, v140, s85, v226
	v_add_f32_e32 v137, v137, v155
	v_mul_f32_e32 v140, 0xbfb8aa3b, v140
	v_med3_f32 v137, v137, s85, v226
	v_and_b32_e32 v162, 0xffff0000, v173
	v_exp_f32_e32 v145, v140
	v_rcp_f32_e32 v140, v3
	v_add_f32_e32 v3, 1.0, v147
	v_mul_f32_e32 v137, 0xbfb8aa3b, v137
	v_med3_f32 v4, v4, s85, v226
	v_rcp_f32_e32 v147, v3
	v_add_f32_e32 v3, v141, v162
	v_exp_f32_e32 v141, v137
	v_mul_f32_e32 v4, 0xbfb8aa3b, v4
	v_exp_f32_e32 v4, v4
	v_med3_f32 v3, v3, s85, v226
	v_mul_f32_e32 v3, 0xbfb8aa3b, v3
	v_exp_f32_e32 v137, v3
	v_add_f32_e32 v3, 1.0, v141
	v_rcp_f32_e32 v141, v3
	v_pk_add_f32 v[4:5], v[4:5], 1.0 op_sel_hi:[1,0]
	v_pk_add_f32 v[144:145], v[144:145], 1.0 op_sel_hi:[1,0]
	v_pk_mul_f32 v[4:5], v[142:143], v[4:5]
	v_pk_add_f32 v[134:135], v[134:135], 1.0 op_sel_hi:[1,0]
	v_pk_mul_f32 v[10:11], v[10:11], v[4:5]
	v_pk_add_f32 v[4:5], v[136:137], 1.0 op_sel_hi:[1,0]
	v_pk_mul_f32 v[142:143], v[146:147], v[144:145]
	v_pk_mul_f32 v[134:135], v[138:139], v[134:135]
	v_pk_mul_f32 v[4:5], v[140:141], v[4:5]
	v_pk_mul_f32 v[12:13], v[12:13], v[142:143]
	v_pk_mul_f32 v[8:9], v[8:9], v[4:5]
	v_pk_mul_f32 v[6:7], v[6:7], v[134:135]
	s_branch .LBB0_380

; #define LAS __attribute__((address_space(3)))
; __global__ void __launch_bounds__(NTHREADS, 2) mk_fwd(Args args) {
;     extern __shared__ __attribute__((aligned(16))) unsigned char lds_raw[];
;     LAS unsigned char* lds = (LAS unsigned char*)lds_raw;
;     const int tid = threadIdx.x, lane = tid & 63, wave = __builtin_amdgcn_readfirstlane(tid >> 6);
	.amdhsa_kernel _Z6mk_fwd4Args
		.amdhsa_group_segment_fixed_size 0
		.amdhsa_private_segment_fixed_size 0
		.amdhsa_kernarg_size 384
		.amdhsa_user_sgpr_count 2
		.amdhsa_user_sgpr_dispatch_ptr 0
		.amdhsa_user_sgpr_queue_ptr 0
		.amdhsa_user_sgpr_kernarg_segment_ptr 1
		.amdhsa_user_sgpr_dispatch_id 0
		.amdhsa_user_sgpr_kernarg_preload_length 0
		.amdhsa_user_sgpr_kernarg_preload_offset 0
		.amdhsa_user_sgpr_private_segment_size 0
		.amdhsa_uses_dynamic_stack 0
		.amdhsa_enable_private_segment 0
		.amdhsa_system_sgpr_workgroup_id_x 1
		.amdhsa_system_sgpr_workgroup_id_y 0
		.amdhsa_system_sgpr_workgroup_id_z 0
		.amdhsa_system_sgpr_workgroup_info 0
		.amdhsa_system_vgpr_workitem_id 2
		.amdhsa_next_free_vgpr 248
		.amdhsa_next_free_sgpr 98
		.amdhsa_accum_offset 248
		.amdhsa_reserve_vcc 1
		.amdhsa_float_round_mode_32 0
		.amdhsa_float_round_mode_16_64 0
		.amdhsa_float_denorm_mode_32 3
		.amdhsa_float_denorm_mode_16_64 3
		.amdhsa_dx10_clamp 1
		.amdhsa_ieee_mode 1
		.amdhsa_fp16_overflow 0
		.amdhsa_tg_split 0
		.amdhsa_exception_fp_ieee_invalid_op 0
		.amdhsa_exception_fp_denorm_src 0
		.amdhsa_exception_fp_ieee_div_zero 0
		.amdhsa_exception_fp_ieee_overflow 0
		.amdhsa_exception_fp_ieee_underflow 0
		.amdhsa_exception_fp_ieee_inexact 0
		.amdhsa_exception_int_div_zero 0
	.end_amdhsa_kernel

; #define LAS __attribute__((address_space(3)))
; __global__ void __launch_bounds__(NTHREADS, 2) mk_fwd(Args args) {
;     extern __shared__ __attribute__((aligned(16))) unsigned char lds_raw[];
;     LAS unsigned char* lds = (LAS unsigned char*)lds_raw;
;     const int tid = threadIdx.x, lane = tid & 63, wave = __builtin_amdgcn_readfirstlane(tid >> 6);
.Lfunc_end0:
	.size	_Z6mk_fwd4Args, .Lfunc_end0-_Z6mk_fwd4Args
	.set _Z6mk_fwd4Args.num_vgpr, 248
	.set _Z6mk_fwd4Args.num_agpr, 0
	.set _Z6mk_fwd4Args.numbered_sgpr, 98
	.set _Z6mk_fwd4Args.num_named_barrier, 0
	.set _Z6mk_fwd4Args.private_seg_size, 0
	.set _Z6mk_fwd4Args.uses_vcc, 1
	.set _Z6mk_fwd4Args.uses_flat_scratch, 0
	.set _Z6mk_fwd4Args.has_dyn_sized_stack, 0
	.set _Z6mk_fwd4Args.has_recursion, 0
	.set _Z6mk_fwd4Args.has_indirect_call, 0

; #define LAS __attribute__((address_space(3)))
; __global__ void __launch_bounds__(NTHREADS, 2) mk_fwd(Args args) {
;     extern __shared__ __attribute__((aligned(16))) unsigned char lds_raw[];
;     LAS unsigned char* lds = (LAS unsigned char*)lds_raw;
;     const int tid = threadIdx.x, lane = tid & 63, wave = __builtin_amdgcn_readfirstlane(tid >> 6);
amdhsa.kernels:
  - .agpr_count:     0
    .args:
      - .offset:         0
        .size:           128
        .value_kind:     by_value
      - .offset:         128
        .size:           4
        .value_kind:     hidden_block_count_x
      - .offset:         132
        .size:           4
        .value_kind:     hidden_block_count_y
      - .offset:         136
        .size:           4
        .value_kind:     hidden_block_count_z
      - .offset:         140
        .size:           2
        .value_kind:     hidden_group_size_x
      - .offset:         142
        .size:           2
        .value_kind:     hidden_group_size_y
      - .offset:         144
        .size:           2
        .value_kind:     hidden_group_size_z
      - .offset:         146
        .size:           2
        .value_kind:     hidden_remainder_x
      - .offset:         148
        .size:           2
        .value_kind:     hidden_remainder_y
      - .offset:         150
        .size:           2
        .value_kind:     hidden_remainder_z
      - .offset:         168
        .size:           8
        .value_kind:     hidden_global_offset_x
      - .offset:         176
        .size:           8
        .value_kind:     hidden_global_offset_y
      - .offset:         184
        .size:           8
        .value_kind:     hidden_global_offset_z
      - .offset:         192
        .size:           2
        .value_kind:     hidden_grid_dims
      - .offset:         216
        .size:           8
        .value_kind:     hidden_multigrid_sync_arg
      - .offset:         248
        .size:           4
        .value_kind:     hidden_dynamic_lds_size
    .group_segment_fixed_size: 0
    .kernarg_segment_align: 8
    .kernarg_segment_size: 384
    .language:       OpenCL C
    .language_version:
      - 2
      - 0
    .max_flat_workgroup_size: 512
    .name:           _Z6mk_fwd4Args
    .private_segment_fixed_size: 0
    .sgpr_count:     104
    .sgpr_spill_count: 15
    .symbol:         _Z6mk_fwd4Args.kd
    .uniform_work_group_size: 1
    .uses_dynamic_stack: false
    .vgpr_count:     248
    .vgpr_spill_count: 0
    .wavefront_size: 64
